# speedup vs baseline: 1.0058x; 1.0058x over previous
.LBB0_732:
	v_lshl_add_u32 v212, s72, 8, v222
	v_ashrrev_i32_e32 v213, 31, v212
	v_lshl_or_b32 v88, s33, 8, v224
	v_lshlrev_b64 v[90:91], 12, v[212:213]
	v_lshl_add_u64 v[90:91], s[30:31], 0, v[90:91]
	v_ashrrev_i32_e32 v89, 31, v88
	v_lshl_add_u64 v[210:211], v[88:89], 1, v[90:91]
	global_load_dwordx4 v[228:231], v[210:211], off
	global_load_dwordx4 v[186:189], v[210:211], off offset:256
	v_add_co_u32_e32 v88, vcc, 0x10000, v210
	v_readlane_b32 s8, v237, 51
	s_nop 0
	v_addc_co_u32_e32 v89, vcc, 0, v211, vcc
	v_readlane_b32 s11, v237, 54
	global_load_dwordx4 v[182:185], v[88:89], off
	global_load_dwordx4 v[178:181], v[88:89], off offset:256
	v_add_co_u32_e32 v88, vcc, s11, v210
	s_mov_b32 s8, 0x80000
	s_nop 0
	v_addc_co_u32_e32 v89, vcc, 0, v211, vcc
	global_load_dwordx4 v[174:177], v[88:89], off
	global_load_dwordx4 v[170:173], v[88:89], off offset:256
	v_add_co_u32_e32 v88, vcc, 0x30000, v210
	v_and_b32_e32 v227, 64, v214
	s_nop 0
	v_addc_co_u32_e32 v89, vcc, 0, v211, vcc
	global_load_dwordx4 v[166:169], v[88:89], off
	global_load_dwordx4 v[162:165], v[88:89], off offset:256
	v_add_co_u32_e32 v88, vcc, s8, v210
	s_mov_b32 s8, 0xb0000
	s_nop 0
	v_addc_co_u32_e32 v89, vcc, 0, v211, vcc
	global_load_dwordx4 v[154:157], v[88:89], off
	global_load_dwordx4 v[146:149], v[88:89], off offset:256
	v_add_co_u32_e32 v88, vcc, 0x90000, v210
	v_xor_b32_e32 v226, 16, v214
	s_nop 0
	v_addc_co_u32_e32 v89, vcc, 0, v211, vcc
	global_load_dwordx4 v[138:141], v[88:89], off
	global_load_dwordx4 v[130:133], v[88:89], off offset:256
	v_add_co_u32_e32 v88, vcc, 0xa0000, v210
	v_add_u32_e32 v227, 64, v227
	s_nop 0
	v_addc_co_u32_e32 v89, vcc, 0, v211, vcc
	global_load_dwordx4 v[116:119], v[88:89], off
	global_load_dwordx4 v[104:107], v[88:89], off offset:256
	v_add_co_u32_e32 v88, vcc, s8, v210
	v_xor_b32_e32 v232, 32, v214
	s_nop 0
	v_addc_co_u32_e32 v89, vcc, 0, v211, vcc
	global_load_dwordx4 v[96:99], v[88:89], off
	s_nop 0
	global_load_dwordx4 v[88:91], v[88:89], off offset:256
	v_cmp_lt_i32_e32 vcc, v226, v227
	v_readlane_b32 s9, v237, 52
	v_readlane_b32 s10, v237, 53
	v_cndmask_b32_e32 v226, v214, v226, vcc
	v_cmp_lt_i32_e32 vcc, v232, v227
	v_lshlrev_b32_e32 v226, 2, v226
	s_waitcnt vmcnt(0)
	v_and_b32_e32 v233, 0xffff0000, v228
	v_cndmask_b32_e32 v227, v214, v232, vcc
	v_lshlrev_b32_e32 v232, 16, v228
	v_lshlrev_b32_e32 v228, 16, v229
	v_and_b32_e32 v229, 0xffff0000, v229
	v_pk_add_f32 v[160:161], v[160:161], v[228:229]
	v_lshlrev_b32_e32 v228, 16, v230
	v_and_b32_e32 v229, 0xffff0000, v230
	v_pk_add_f32 v[228:229], v[150:151], v[228:229]
	v_lshlrev_b32_e32 v150, 16, v231
	v_and_b32_e32 v151, 0xffff0000, v231
	v_pk_add_f32 v[158:159], v[158:159], v[232:233]
	v_pk_add_f32 v[230:231], v[152:153], v[150:151]
	v_cvt_pk_bf16_f32 v150, v158, v159
	v_cvt_pk_bf16_f32 v151, v160, v161
	v_cvt_pk_bf16_f32 v152, v228, v229
	v_cvt_pk_bf16_f32 v153, v230, v231
	global_store_dwordx4 v[210:211], v[150:153], off sc1
	v_lshlrev_b32_e32 v227, 2, v227
	s_nop 0
	v_pk_mul_f32 v[150:151], v[158:159], v[158:159]
	v_pk_mul_f32 v[158:159], v[228:229], v[228:229]
	v_lshlrev_b32_e32 v228, 16, v186
	v_and_b32_e32 v229, 0xffff0000, v186
	v_lshlrev_b32_e32 v186, 16, v187
	v_and_b32_e32 v187, 0xffff0000, v187
	v_pk_add_f32 v[144:145], v[144:145], v[186:187]
	v_lshlrev_b32_e32 v186, 16, v188
	v_and_b32_e32 v187, 0xffff0000, v188
	v_pk_add_f32 v[186:187], v[134:135], v[186:187]
	v_lshlrev_b32_e32 v134, 16, v189
	v_and_b32_e32 v135, 0xffff0000, v189
	v_pk_add_f32 v[142:143], v[142:143], v[228:229]
	v_pk_add_f32 v[188:189], v[136:137], v[134:135]
	v_cvt_pk_bf16_f32 v134, v142, v143
	v_cvt_pk_bf16_f32 v135, v144, v145
	v_cvt_pk_bf16_f32 v136, v186, v187
	v_cvt_pk_bf16_f32 v137, v188, v189
	global_store_dwordx4 v[210:211], v[134:137], off offset:256 sc1
	v_pk_mul_f32 v[152:153], v[160:161], v[160:161]
	v_pk_mul_f32 v[160:161], v[230:231], v[230:231]
	v_pk_mul_f32 v[134:135], v[142:143], v[142:143]
	v_pk_mul_f32 v[136:137], v[144:145], v[144:145]
	v_add_f32_e32 v134, v134, v135
	v_add_f32_e32 v136, v136, v137
	v_pk_mul_f32 v[142:143], v[186:187], v[186:187]
	v_pk_mul_f32 v[144:145], v[188:189], v[188:189]
	v_add_f32_e32 v134, v134, v136
	v_add_f32_e32 v135, v160, v161
	v_add_f32_e32 v136, v158, v159
	v_add_f32_e32 v144, v144, v145
	v_add_f32_e32 v142, v142, v143
	v_add_f32_e32 v135, v136, v135
	v_add_f32_e32 v136, v152, v153
	v_add_f32_e32 v137, v150, v151
	v_add_f32_e32 v142, v142, v144
	v_add_f32_e32 v136, v137, v136
	v_add_f32_e32 v134, v134, v142
	v_add_f32_e32 v135, v136, v135
	v_add_f32_e32 v134, v135, v134
	v_mov_b32_e32 v242, v134
	v_mov_b32_e32 v243, v134
	s_nop 1
	v_permlane16_swap_b32_e32 v242, v243
	v_add_f32_e32 v136, v242, v243
	v_mov_b32_e32 v242, v136
	v_mov_b32_e32 v243, v136
	s_nop 1
	v_permlane32_swap_b32_e32 v242, v243
	v_lshl_add_u64 v[134:135], v[212:213], 3, s[42:43]
	s_and_saveexec_b64 s[8:9], s[38:39]
	s_cbranch_execz .LBB0_734
	s_waitcnt lgkmcnt(0)
	v_add_f32_e32 v136, v242, v243
	v_mul_f32_e32 v136, 0x4b800000, v136
	v_trunc_f32_e32 v136, v136
	v_mul_f32_e32 v137, 0x2f800000, v136
	v_floor_f32_e32 v137, v137
	v_fmac_f32_e32 v136, 0xcf800000, v137
	v_cvt_u32_f32_e32 v136, v136
	v_cvt_u32_f32_e32 v137, v137
	global_atomic_add_x2 v[134:135], v[136:137], off
.LBB0_734:
	s_or_b64 exec, exec, s[8:9]
	v_lshlrev_b32_e32 v144, 16, v182
	v_and_b32_e32 v145, 0xffff0000, v182
	v_pk_add_f32 v[124:125], v[124:125], v[144:145]
	v_lshlrev_b32_e32 v144, 16, v183
	v_and_b32_e32 v145, 0xffff0000, v183
	v_pk_add_f32 v[126:127], v[126:127], v[144:145]
	v_lshlrev_b32_e32 v144, 16, v184
	v_and_b32_e32 v145, 0xffff0000, v184
	v_pk_add_f32 v[144:145], v[120:121], v[144:145]
	v_lshlrev_b32_e32 v120, 16, v185
	v_and_b32_e32 v121, 0xffff0000, v185
	s_mov_b64 s[8:9], 0x10000
	v_pk_add_f32 v[150:151], v[122:123], v[120:121]
	s_waitcnt lgkmcnt(0)
	v_lshl_add_u64 v[136:137], v[210:211], 0, s[8:9]
	v_cvt_pk_bf16_f32 v120, v124, v125
	v_cvt_pk_bf16_f32 v121, v126, v127
	v_cvt_pk_bf16_f32 v122, v144, v145
	v_cvt_pk_bf16_f32 v123, v150, v151
	global_store_dwordx4 v[136:137], v[120:123], off sc1
	v_lshlrev_b32_e32 v136, 16, v178
	v_and_b32_e32 v137, 0xffff0000, v178
	v_pk_add_f32 v[112:113], v[112:113], v[136:137]
	v_lshlrev_b32_e32 v136, 16, v179
	v_and_b32_e32 v137, 0xffff0000, v179
	v_pk_add_f32 v[114:115], v[114:115], v[136:137]
	v_lshlrev_b32_e32 v136, 16, v180
	v_and_b32_e32 v137, 0xffff0000, v180
	v_pk_add_f32 v[136:137], v[108:109], v[136:137]
	v_lshlrev_b32_e32 v108, 16, v181
	v_and_b32_e32 v109, 0xffff0000, v181
	s_mov_b64 s[8:9], 0x10100
	v_pk_mul_f32 v[120:121], v[124:125], v[124:125]
	v_pk_mul_f32 v[124:125], v[144:145], v[144:145]
	v_pk_add_f32 v[144:145], v[110:111], v[108:109]
	v_lshl_add_u64 v[142:143], v[210:211], 0, s[8:9]
	v_cvt_pk_bf16_f32 v108, v112, v113
	v_cvt_pk_bf16_f32 v109, v114, v115
	v_cvt_pk_bf16_f32 v110, v136, v137
	v_cvt_pk_bf16_f32 v111, v144, v145
	global_store_dwordx4 v[142:143], v[108:111], off sc1
	v_pk_mul_f32 v[122:123], v[126:127], v[126:127]
	v_pk_mul_f32 v[126:127], v[150:151], v[150:151]
	v_pk_mul_f32 v[108:109], v[112:113], v[112:113]
	v_pk_mul_f32 v[110:111], v[114:115], v[114:115]
	v_add_f32_e32 v108, v108, v109
	v_add_f32_e32 v110, v110, v111
	v_pk_mul_f32 v[112:113], v[136:137], v[136:137]
	v_pk_mul_f32 v[114:115], v[144:145], v[144:145]
	v_add_f32_e32 v108, v108, v110
	v_add_f32_e32 v109, v126, v127
	v_add_f32_e32 v110, v124, v125
	v_add_f32_e32 v114, v114, v115
	v_add_f32_e32 v112, v112, v113
	v_add_f32_e32 v109, v110, v109
	v_add_f32_e32 v110, v122, v123
	v_add_f32_e32 v111, v120, v121
	v_add_f32_e32 v112, v112, v114
	v_add_f32_e32 v110, v111, v110
	v_add_f32_e32 v108, v108, v112
	v_add_f32_e32 v109, v110, v109
	v_add_f32_e32 v108, v109, v108
	v_mov_b32_e32 v242, v108
	v_mov_b32_e32 v243, v108
	s_nop 1
	v_permlane16_swap_b32_e32 v242, v243
	v_add_f32_e32 v108, v242, v243
	v_mov_b32_e32 v242, v108
	v_mov_b32_e32 v243, v108
	s_nop 1
	v_permlane32_swap_b32_e32 v242, v243
	s_and_saveexec_b64 s[8:9], s[38:39]
	s_cbranch_execz .LBB0_736
	s_waitcnt lgkmcnt(0)
	v_add_f32_e32 v108, v242, v243
	v_mul_f32_e32 v108, 0x4b800000, v108
	v_trunc_f32_e32 v108, v108
	v_mul_f32_e32 v109, 0x2f800000, v108
	v_floor_f32_e32 v109, v109
	v_fmac_f32_e32 v108, 0xcf800000, v109
	v_cvt_u32_f32_e32 v108, v108
	v_cvt_u32_f32_e32 v109, v109
	global_atomic_add_x2 v[134:135], v[108:109], off offset:128
.LBB0_736:
	s_or_b64 exec, exec, s[8:9]
	v_lshlrev_b32_e32 v112, 16, v174
	v_and_b32_e32 v113, 0xffff0000, v174
	v_pk_add_f32 v[100:101], v[100:101], v[112:113]
	v_lshlrev_b32_e32 v112, 16, v175
	v_and_b32_e32 v113, 0xffff0000, v175
	v_pk_add_f32 v[102:103], v[102:103], v[112:113]
	v_lshlrev_b32_e32 v112, 16, v176
	v_and_b32_e32 v113, 0xffff0000, v176
	v_pk_add_f32 v[112:113], v[92:93], v[112:113]
	v_lshlrev_b32_e32 v92, 16, v177
	v_and_b32_e32 v93, 0xffff0000, v177
	s_mov_b64 s[8:9], 0x20000
	v_pk_add_f32 v[114:115], v[94:95], v[92:93]
	s_waitcnt lgkmcnt(0)
	v_lshl_add_u64 v[108:109], v[210:211], 0, s[8:9]
	v_cvt_pk_bf16_f32 v92, v100, v101
	v_cvt_pk_bf16_f32 v93, v102, v103
	v_cvt_pk_bf16_f32 v94, v112, v113
	v_cvt_pk_bf16_f32 v95, v114, v115
	global_store_dwordx4 v[108:109], v[92:95], off sc1
	v_lshlrev_b32_e32 v108, 16, v170
	v_and_b32_e32 v109, 0xffff0000, v170
	v_pk_add_f32 v[84:85], v[84:85], v[108:109]
	v_lshlrev_b32_e32 v108, 16, v171
	v_and_b32_e32 v109, 0xffff0000, v171
	v_pk_add_f32 v[86:87], v[86:87], v[108:109]
	v_lshlrev_b32_e32 v108, 16, v172
	v_and_b32_e32 v109, 0xffff0000, v172
	v_pk_add_f32 v[108:109], v[80:81], v[108:109]
	v_lshlrev_b32_e32 v80, 16, v173
	v_and_b32_e32 v81, 0xffff0000, v173
	s_mov_b64 s[8:9], 0x20100
	v_pk_mul_f32 v[92:93], v[100:101], v[100:101]
	v_pk_mul_f32 v[100:101], v[112:113], v[112:113]
	v_pk_add_f32 v[112:113], v[82:83], v[80:81]
	v_lshl_add_u64 v[110:111], v[210:211], 0, s[8:9]
	v_cvt_pk_bf16_f32 v80, v84, v85
	v_cvt_pk_bf16_f32 v81, v86, v87
	v_cvt_pk_bf16_f32 v82, v108, v109
	v_cvt_pk_bf16_f32 v83, v112, v113
	global_store_dwordx4 v[110:111], v[80:83], off sc1
	v_pk_mul_f32 v[94:95], v[102:103], v[102:103]
	v_pk_mul_f32 v[102:103], v[114:115], v[114:115]
	v_pk_mul_f32 v[80:81], v[84:85], v[84:85]
	v_pk_mul_f32 v[82:83], v[86:87], v[86:87]
	v_add_f32_e32 v80, v80, v81
	v_add_f32_e32 v82, v82, v83
	v_pk_mul_f32 v[84:85], v[108:109], v[108:109]
	v_pk_mul_f32 v[86:87], v[112:113], v[112:113]
	v_add_f32_e32 v80, v80, v82
	v_add_f32_e32 v81, v102, v103
	v_add_f32_e32 v82, v100, v101
	v_add_f32_e32 v86, v86, v87
	v_add_f32_e32 v84, v84, v85
	v_add_f32_e32 v81, v82, v81
	v_add_f32_e32 v82, v94, v95
	v_add_f32_e32 v83, v92, v93
	v_add_f32_e32 v84, v84, v86
	v_add_f32_e32 v82, v83, v82
	v_add_f32_e32 v80, v80, v84
	v_add_f32_e32 v81, v82, v81
	v_add_f32_e32 v80, v81, v80
	v_mov_b32_e32 v242, v80
	v_mov_b32_e32 v243, v80
	s_nop 1
	v_permlane16_swap_b32_e32 v242, v243
	v_add_f32_e32 v80, v242, v243
	v_mov_b32_e32 v242, v80
	v_mov_b32_e32 v243, v80
	s_nop 1
	v_permlane32_swap_b32_e32 v242, v243
	s_and_saveexec_b64 s[8:9], s[38:39]
	s_mov_b64 s[28:29], s[34:35]
	s_cbranch_execz .LBB0_738
	s_waitcnt lgkmcnt(0)
	v_add_f32_e32 v80, v242, v243
	v_mul_f32_e32 v80, 0x4b800000, v80
	v_trunc_f32_e32 v80, v80
	v_mul_f32_e32 v81, 0x2f800000, v80
	v_floor_f32_e32 v81, v81
	v_fmac_f32_e32 v80, 0xcf800000, v81
	v_cvt_u32_f32_e32 v80, v80
	v_cvt_u32_f32_e32 v81, v81
	global_atomic_add_x2 v[134:135], v[80:81], off offset:256
.LBB0_738:
	s_or_b64 exec, exec, s[8:9]
	v_lshlrev_b32_e32 v84, 16, v166
	v_and_b32_e32 v85, 0xffff0000, v166
	v_pk_add_f32 v[76:77], v[76:77], v[84:85]
	v_lshlrev_b32_e32 v84, 16, v167
	v_and_b32_e32 v85, 0xffff0000, v167
	v_pk_add_f32 v[78:79], v[78:79], v[84:85]
	v_lshlrev_b32_e32 v84, 16, v168
	v_and_b32_e32 v85, 0xffff0000, v168
	v_pk_add_f32 v[84:85], v[72:73], v[84:85]
	v_lshlrev_b32_e32 v72, 16, v169
	v_and_b32_e32 v73, 0xffff0000, v169
	s_mov_b64 s[8:9], 0x30000
	v_pk_add_f32 v[86:87], v[74:75], v[72:73]
	s_waitcnt lgkmcnt(0)
	v_lshl_add_u64 v[80:81], v[210:211], 0, s[8:9]
	v_cvt_pk_bf16_f32 v72, v76, v77
	v_cvt_pk_bf16_f32 v73, v78, v79
	v_cvt_pk_bf16_f32 v74, v84, v85
	v_cvt_pk_bf16_f32 v75, v86, v87
	global_store_dwordx4 v[80:81], v[72:75], off sc1
	v_lshlrev_b32_e32 v80, 16, v162
	v_and_b32_e32 v81, 0xffff0000, v162
	v_pk_add_f32 v[68:69], v[68:69], v[80:81]
	v_lshlrev_b32_e32 v80, 16, v163
	v_and_b32_e32 v81, 0xffff0000, v163
	v_pk_add_f32 v[70:71], v[70:71], v[80:81]
	v_lshlrev_b32_e32 v80, 16, v164
	v_and_b32_e32 v81, 0xffff0000, v164
	v_pk_add_f32 v[80:81], v[64:65], v[80:81]
	v_lshlrev_b32_e32 v64, 16, v165
	v_and_b32_e32 v65, 0xffff0000, v165
	s_mov_b64 s[8:9], 0x30100
	v_pk_mul_f32 v[72:73], v[76:77], v[76:77]
	v_pk_mul_f32 v[76:77], v[84:85], v[84:85]
	v_pk_add_f32 v[84:85], v[66:67], v[64:65]
	v_lshl_add_u64 v[82:83], v[210:211], 0, s[8:9]
	v_cvt_pk_bf16_f32 v64, v68, v69
	v_cvt_pk_bf16_f32 v65, v70, v71
	v_cvt_pk_bf16_f32 v66, v80, v81
	v_cvt_pk_bf16_f32 v67, v84, v85
	global_store_dwordx4 v[82:83], v[64:67], off sc1
	v_pk_mul_f32 v[74:75], v[78:79], v[78:79]
	v_pk_mul_f32 v[78:79], v[86:87], v[86:87]
	v_pk_mul_f32 v[64:65], v[68:69], v[68:69]
	v_pk_mul_f32 v[66:67], v[70:71], v[70:71]
	v_add_f32_e32 v64, v64, v65
	v_add_f32_e32 v66, v66, v67
	v_pk_mul_f32 v[68:69], v[80:81], v[80:81]
	v_pk_mul_f32 v[70:71], v[84:85], v[84:85]
	v_add_f32_e32 v64, v64, v66
	v_add_f32_e32 v65, v78, v79
	v_add_f32_e32 v66, v76, v77
	v_add_f32_e32 v70, v70, v71
	v_add_f32_e32 v68, v68, v69
	v_add_f32_e32 v65, v66, v65
	v_add_f32_e32 v66, v74, v75
	v_add_f32_e32 v67, v72, v73
	v_add_f32_e32 v68, v68, v70
	v_add_f32_e32 v66, v67, v66
	v_add_f32_e32 v64, v64, v68
	v_add_f32_e32 v65, v66, v65
	v_add_f32_e32 v64, v65, v64
	v_mov_b32_e32 v242, v64
	v_mov_b32_e32 v243, v64
	s_nop 1
	v_permlane16_swap_b32_e32 v242, v243
	v_add_f32_e32 v64, v242, v243
	v_mov_b32_e32 v242, v64
	v_mov_b32_e32 v243, v64
	s_nop 1
	v_permlane32_swap_b32_e32 v242, v243
	s_and_saveexec_b64 s[8:9], s[38:39]
	s_cbranch_execz .LBB0_740
	s_waitcnt lgkmcnt(0)
	v_add_f32_e32 v64, v242, v243
	v_mul_f32_e32 v64, 0x4b800000, v64
	v_trunc_f32_e32 v64, v64
	v_mul_f32_e32 v65, 0x2f800000, v64
	v_floor_f32_e32 v65, v65
	v_fmac_f32_e32 v64, 0xcf800000, v65
	v_cvt_u32_f32_e32 v64, v64
	v_cvt_u32_f32_e32 v65, v65
	global_atomic_add_x2 v[134:135], v[64:65], off offset:384
.LBB0_740:
	s_or_b64 exec, exec, s[8:9]
	v_lshlrev_b32_e32 v68, 16, v154
	v_and_b32_e32 v69, 0xffff0000, v154
	v_pk_add_f32 v[60:61], v[60:61], v[68:69]
	v_lshlrev_b32_e32 v68, 16, v155
	v_and_b32_e32 v69, 0xffff0000, v155
	v_pk_add_f32 v[62:63], v[62:63], v[68:69]
	v_lshlrev_b32_e32 v68, 16, v156
	v_and_b32_e32 v69, 0xffff0000, v156
	v_pk_add_f32 v[68:69], v[56:57], v[68:69]
	v_lshlrev_b32_e32 v56, 16, v157
	v_and_b32_e32 v57, 0xffff0000, v157
	s_mov_b64 s[8:9], 0x80000
	v_pk_add_f32 v[70:71], v[58:59], v[56:57]
	s_waitcnt lgkmcnt(0)
	v_lshl_add_u64 v[64:65], v[210:211], 0, s[8:9]
	v_cvt_pk_bf16_f32 v56, v60, v61
	v_cvt_pk_bf16_f32 v57, v62, v63
	v_cvt_pk_bf16_f32 v58, v68, v69
	v_cvt_pk_bf16_f32 v59, v70, v71
	global_store_dwordx4 v[64:65], v[56:59], off sc1
	v_lshlrev_b32_e32 v64, 16, v146
	v_and_b32_e32 v65, 0xffff0000, v146
	v_pk_add_f32 v[52:53], v[52:53], v[64:65]
	v_lshlrev_b32_e32 v64, 16, v147
	v_and_b32_e32 v65, 0xffff0000, v147
	v_pk_add_f32 v[54:55], v[54:55], v[64:65]
	v_lshlrev_b32_e32 v64, 16, v148
	v_and_b32_e32 v65, 0xffff0000, v148
	v_pk_add_f32 v[64:65], v[48:49], v[64:65]
	v_lshlrev_b32_e32 v48, 16, v149
	v_and_b32_e32 v49, 0xffff0000, v149
	s_mov_b64 s[8:9], 0x80100
	v_pk_mul_f32 v[56:57], v[60:61], v[60:61]
	v_pk_mul_f32 v[60:61], v[68:69], v[68:69]
	v_pk_add_f32 v[68:69], v[50:51], v[48:49]
	v_lshl_add_u64 v[66:67], v[210:211], 0, s[8:9]
	v_cvt_pk_bf16_f32 v48, v52, v53
	v_cvt_pk_bf16_f32 v49, v54, v55
	v_cvt_pk_bf16_f32 v50, v64, v65
	v_cvt_pk_bf16_f32 v51, v68, v69
	global_store_dwordx4 v[66:67], v[48:51], off sc1
	v_pk_mul_f32 v[58:59], v[62:63], v[62:63]
	v_pk_mul_f32 v[62:63], v[70:71], v[70:71]
	v_pk_mul_f32 v[48:49], v[52:53], v[52:53]
	v_pk_mul_f32 v[50:51], v[54:55], v[54:55]
	v_add_f32_e32 v48, v48, v49
	v_add_f32_e32 v50, v50, v51
	v_pk_mul_f32 v[52:53], v[64:65], v[64:65]
	v_pk_mul_f32 v[54:55], v[68:69], v[68:69]
	v_add_f32_e32 v48, v48, v50
	v_add_f32_e32 v49, v62, v63
	v_add_f32_e32 v50, v60, v61
	v_add_f32_e32 v54, v54, v55
	v_add_f32_e32 v52, v52, v53
	v_add_f32_e32 v49, v50, v49
	v_add_f32_e32 v50, v58, v59
	v_add_f32_e32 v51, v56, v57
	v_add_f32_e32 v52, v52, v54
	v_add_f32_e32 v50, v51, v50
	v_add_f32_e32 v48, v48, v52
	v_add_f32_e32 v49, v50, v49
	v_add_f32_e32 v48, v49, v48
	v_mov_b32_e32 v242, v48
	v_mov_b32_e32 v243, v48
	s_nop 1
	v_permlane16_swap_b32_e32 v242, v243
	v_add_f32_e32 v48, v242, v243
	v_mov_b32_e32 v242, v48
	v_mov_b32_e32 v243, v48
	s_nop 1
	v_permlane32_swap_b32_e32 v242, v243
	s_and_saveexec_b64 s[8:9], s[38:39]
	s_cbranch_execz .LBB0_742
	s_waitcnt lgkmcnt(0)
	v_add_f32_e32 v48, v242, v243
	v_mul_f32_e32 v48, 0x4b800000, v48
	v_trunc_f32_e32 v48, v48
	v_mul_f32_e32 v49, 0x2f800000, v48
	v_floor_f32_e32 v49, v49
	v_fmac_f32_e32 v48, 0xcf800000, v49
	v_cvt_u32_f32_e32 v48, v48
	v_cvt_u32_f32_e32 v49, v49
	global_atomic_add_x2 v[134:135], v[48:49], off offset:1024
.LBB0_742:
	s_or_b64 exec, exec, s[8:9]
	v_lshlrev_b32_e32 v52, 16, v138
	v_and_b32_e32 v53, 0xffff0000, v138
	v_pk_add_f32 v[44:45], v[44:45], v[52:53]
	v_lshlrev_b32_e32 v52, 16, v139
	v_and_b32_e32 v53, 0xffff0000, v139
	v_pk_add_f32 v[46:47], v[46:47], v[52:53]
	v_lshlrev_b32_e32 v52, 16, v140
	v_and_b32_e32 v53, 0xffff0000, v140
	v_pk_add_f32 v[52:53], v[40:41], v[52:53]
	v_lshlrev_b32_e32 v40, 16, v141
	v_and_b32_e32 v41, 0xffff0000, v141
	s_mov_b64 s[8:9], 0x90000
	v_pk_add_f32 v[54:55], v[42:43], v[40:41]
	s_waitcnt lgkmcnt(0)
	v_lshl_add_u64 v[48:49], v[210:211], 0, s[8:9]
	v_cvt_pk_bf16_f32 v40, v44, v45
	v_cvt_pk_bf16_f32 v41, v46, v47
	v_cvt_pk_bf16_f32 v42, v52, v53
	v_cvt_pk_bf16_f32 v43, v54, v55
	global_store_dwordx4 v[48:49], v[40:43], off sc1
	v_lshlrev_b32_e32 v48, 16, v130
	v_and_b32_e32 v49, 0xffff0000, v130
	v_pk_add_f32 v[36:37], v[36:37], v[48:49]
	v_lshlrev_b32_e32 v48, 16, v131
	v_and_b32_e32 v49, 0xffff0000, v131
	v_pk_add_f32 v[38:39], v[38:39], v[48:49]
	v_lshlrev_b32_e32 v48, 16, v132
	v_and_b32_e32 v49, 0xffff0000, v132
	v_pk_add_f32 v[48:49], v[32:33], v[48:49]
	v_lshlrev_b32_e32 v32, 16, v133
	v_and_b32_e32 v33, 0xffff0000, v133
	s_mov_b64 s[8:9], 0x90100
	v_pk_mul_f32 v[40:41], v[44:45], v[44:45]
	v_pk_mul_f32 v[44:45], v[52:53], v[52:53]
	v_pk_add_f32 v[52:53], v[34:35], v[32:33]
	v_lshl_add_u64 v[50:51], v[210:211], 0, s[8:9]
	v_cvt_pk_bf16_f32 v32, v36, v37
	v_cvt_pk_bf16_f32 v33, v38, v39
	v_cvt_pk_bf16_f32 v34, v48, v49
	v_cvt_pk_bf16_f32 v35, v52, v53
	global_store_dwordx4 v[50:51], v[32:35], off sc1
	v_pk_mul_f32 v[42:43], v[46:47], v[46:47]
	v_pk_mul_f32 v[46:47], v[54:55], v[54:55]
	v_pk_mul_f32 v[32:33], v[36:37], v[36:37]
	v_pk_mul_f32 v[34:35], v[38:39], v[38:39]
	v_add_f32_e32 v32, v32, v33
	v_add_f32_e32 v34, v34, v35
	v_pk_mul_f32 v[36:37], v[48:49], v[48:49]
	v_pk_mul_f32 v[38:39], v[52:53], v[52:53]
	v_add_f32_e32 v32, v32, v34
	v_add_f32_e32 v33, v46, v47
	v_add_f32_e32 v34, v44, v45
	v_add_f32_e32 v38, v38, v39
	v_add_f32_e32 v36, v36, v37
	v_add_f32_e32 v33, v34, v33
	v_add_f32_e32 v34, v42, v43
	v_add_f32_e32 v35, v40, v41
	v_add_f32_e32 v36, v36, v38
	v_add_f32_e32 v34, v35, v34
	v_add_f32_e32 v32, v32, v36
	v_add_f32_e32 v33, v34, v33
	v_add_f32_e32 v32, v33, v32
	v_mov_b32_e32 v242, v32
	v_mov_b32_e32 v243, v32
	s_nop 1
	v_permlane16_swap_b32_e32 v242, v243
	v_add_f32_e32 v32, v242, v243
	v_mov_b32_e32 v242, v32
	v_mov_b32_e32 v243, v32
	s_nop 1
	v_permlane32_swap_b32_e32 v242, v243
	s_and_saveexec_b64 s[8:9], s[38:39]
	s_cbranch_execz .LBB0_744
	s_waitcnt lgkmcnt(0)
	v_add_f32_e32 v32, v242, v243
	v_mul_f32_e32 v32, 0x4b800000, v32
	v_trunc_f32_e32 v32, v32
	v_mul_f32_e32 v33, 0x2f800000, v32
	v_floor_f32_e32 v33, v33
	v_fmac_f32_e32 v32, 0xcf800000, v33
	v_cvt_u32_f32_e32 v32, v32
	v_cvt_u32_f32_e32 v33, v33
	global_atomic_add_x2 v[134:135], v[32:33], off offset:1152
.LBB0_744:
	s_or_b64 exec, exec, s[8:9]
	v_lshlrev_b32_e32 v36, 16, v116
	v_and_b32_e32 v37, 0xffff0000, v116
	v_pk_add_f32 v[28:29], v[28:29], v[36:37]
	v_lshlrev_b32_e32 v36, 16, v117
	v_and_b32_e32 v37, 0xffff0000, v117
	v_pk_add_f32 v[30:31], v[30:31], v[36:37]
	v_lshlrev_b32_e32 v36, 16, v118
	v_and_b32_e32 v37, 0xffff0000, v118
	v_pk_add_f32 v[36:37], v[24:25], v[36:37]
	v_lshlrev_b32_e32 v24, 16, v119
	v_and_b32_e32 v25, 0xffff0000, v119
	s_mov_b64 s[8:9], 0xa0000
	v_pk_add_f32 v[38:39], v[26:27], v[24:25]
	s_waitcnt lgkmcnt(0)
	v_lshl_add_u64 v[32:33], v[210:211], 0, s[8:9]
	v_cvt_pk_bf16_f32 v24, v28, v29
	v_cvt_pk_bf16_f32 v25, v30, v31
	v_cvt_pk_bf16_f32 v26, v36, v37
	v_cvt_pk_bf16_f32 v27, v38, v39
	global_store_dwordx4 v[32:33], v[24:27], off sc1
	v_lshlrev_b32_e32 v32, 16, v104
	v_and_b32_e32 v33, 0xffff0000, v104
	v_pk_add_f32 v[20:21], v[20:21], v[32:33]
	v_lshlrev_b32_e32 v32, 16, v105
	v_and_b32_e32 v33, 0xffff0000, v105
	v_pk_add_f32 v[22:23], v[22:23], v[32:33]
	v_lshlrev_b32_e32 v32, 16, v106
	v_and_b32_e32 v33, 0xffff0000, v106
	v_pk_add_f32 v[32:33], v[16:17], v[32:33]
	v_lshlrev_b32_e32 v16, 16, v107
	v_and_b32_e32 v17, 0xffff0000, v107
	s_mov_b64 s[8:9], 0xa0100
	v_pk_mul_f32 v[24:25], v[28:29], v[28:29]
	v_pk_mul_f32 v[28:29], v[36:37], v[36:37]
	v_pk_add_f32 v[36:37], v[18:19], v[16:17]
	v_lshl_add_u64 v[34:35], v[210:211], 0, s[8:9]
	v_cvt_pk_bf16_f32 v16, v20, v21
	v_cvt_pk_bf16_f32 v17, v22, v23
	v_cvt_pk_bf16_f32 v18, v32, v33
	v_cvt_pk_bf16_f32 v19, v36, v37
	global_store_dwordx4 v[34:35], v[16:19], off sc1
	v_pk_mul_f32 v[26:27], v[30:31], v[30:31]
	v_pk_mul_f32 v[30:31], v[38:39], v[38:39]
	v_pk_mul_f32 v[16:17], v[20:21], v[20:21]
	v_pk_mul_f32 v[18:19], v[22:23], v[22:23]
	v_add_f32_e32 v16, v16, v17
	v_add_f32_e32 v18, v18, v19
	v_pk_mul_f32 v[20:21], v[32:33], v[32:33]
	v_pk_mul_f32 v[22:23], v[36:37], v[36:37]
	v_add_f32_e32 v16, v16, v18
	v_add_f32_e32 v17, v30, v31
	v_add_f32_e32 v18, v28, v29
	v_add_f32_e32 v22, v22, v23
	v_add_f32_e32 v20, v20, v21
	v_add_f32_e32 v17, v18, v17
	v_add_f32_e32 v18, v26, v27
	v_add_f32_e32 v19, v24, v25
	v_add_f32_e32 v20, v20, v22
	v_add_f32_e32 v18, v19, v18
	v_add_f32_e32 v16, v16, v20
	v_add_f32_e32 v17, v18, v17
	v_add_f32_e32 v16, v17, v16
	v_mov_b32_e32 v242, v16
	v_mov_b32_e32 v243, v16
	s_nop 1
	v_permlane16_swap_b32_e32 v242, v243
	v_add_f32_e32 v16, v242, v243
	v_mov_b32_e32 v242, v16
	v_mov_b32_e32 v243, v16
	s_nop 1
	v_permlane32_swap_b32_e32 v242, v243
	s_and_saveexec_b64 s[8:9], s[38:39]
	s_cbranch_execz .LBB0_746
	s_waitcnt lgkmcnt(0)
	v_add_f32_e32 v16, v242, v243
	v_mul_f32_e32 v16, 0x4b800000, v16
	v_trunc_f32_e32 v16, v16
	v_mul_f32_e32 v17, 0x2f800000, v16
	v_floor_f32_e32 v17, v17
	v_fmac_f32_e32 v16, 0xcf800000, v17
	v_cvt_u32_f32_e32 v16, v16
	v_cvt_u32_f32_e32 v17, v17
	global_atomic_add_x2 v[134:135], v[16:17], off offset:1280
.LBB0_746:
	s_or_b64 exec, exec, s[8:9]
	v_lshlrev_b32_e32 v20, 16, v96
	v_and_b32_e32 v21, 0xffff0000, v96
	v_pk_add_f32 v[12:13], v[12:13], v[20:21]
	v_lshlrev_b32_e32 v20, 16, v97
	v_and_b32_e32 v21, 0xffff0000, v97
	v_pk_add_f32 v[14:15], v[14:15], v[20:21]
	v_lshlrev_b32_e32 v20, 16, v98
	v_and_b32_e32 v21, 0xffff0000, v98
	v_pk_add_f32 v[20:21], v[8:9], v[20:21]
	v_lshlrev_b32_e32 v8, 16, v99
	v_and_b32_e32 v9, 0xffff0000, v99
	s_mov_b64 s[8:9], 0xb0000
	v_pk_add_f32 v[22:23], v[10:11], v[8:9]
	s_waitcnt lgkmcnt(0)
	v_lshl_add_u64 v[16:17], v[210:211], 0, s[8:9]
	v_cvt_pk_bf16_f32 v8, v12, v13
	v_cvt_pk_bf16_f32 v9, v14, v15
	v_cvt_pk_bf16_f32 v10, v20, v21
	v_cvt_pk_bf16_f32 v11, v22, v23
	global_store_dwordx4 v[16:17], v[8:11], off sc1
	v_lshlrev_b32_e32 v16, 16, v88
	v_and_b32_e32 v17, 0xffff0000, v88
	v_pk_add_f32 v[4:5], v[4:5], v[16:17]
	v_lshlrev_b32_e32 v16, 16, v89
	v_and_b32_e32 v17, 0xffff0000, v89
	v_pk_add_f32 v[6:7], v[6:7], v[16:17]
	v_lshlrev_b32_e32 v16, 16, v90
	v_and_b32_e32 v17, 0xffff0000, v90
	v_pk_add_f32 v[16:17], v[0:1], v[16:17]
	v_lshlrev_b32_e32 v0, 16, v91
	v_and_b32_e32 v1, 0xffff0000, v91
	s_mov_b64 s[8:9], 0xb0100
	v_pk_mul_f32 v[8:9], v[12:13], v[12:13]
	v_pk_mul_f32 v[12:13], v[20:21], v[20:21]
	v_pk_add_f32 v[20:21], v[2:3], v[0:1]
	v_lshl_add_u64 v[18:19], v[210:211], 0, s[8:9]
	v_cvt_pk_bf16_f32 v0, v4, v5
	v_cvt_pk_bf16_f32 v1, v6, v7
	v_cvt_pk_bf16_f32 v2, v16, v17
	v_cvt_pk_bf16_f32 v3, v20, v21
	global_store_dwordx4 v[18:19], v[0:3], off sc1
	v_pk_mul_f32 v[10:11], v[14:15], v[14:15]
	v_pk_mul_f32 v[14:15], v[22:23], v[22:23]
	v_pk_mul_f32 v[0:1], v[4:5], v[4:5]
	v_pk_mul_f32 v[2:3], v[6:7], v[6:7]
	v_add_f32_e32 v0, v0, v1
	v_add_f32_e32 v2, v2, v3
	v_pk_mul_f32 v[4:5], v[16:17], v[16:17]
	v_pk_mul_f32 v[6:7], v[20:21], v[20:21]
	v_add_f32_e32 v0, v0, v2
	v_add_f32_e32 v1, v14, v15
	v_add_f32_e32 v2, v12, v13
	v_add_f32_e32 v6, v6, v7
	v_add_f32_e32 v4, v4, v5
	v_add_f32_e32 v1, v2, v1
	v_add_f32_e32 v2, v10, v11
	v_add_f32_e32 v3, v8, v9
	v_add_f32_e32 v4, v4, v6
	v_add_f32_e32 v2, v3, v2
	v_add_f32_e32 v0, v0, v4
	v_add_f32_e32 v1, v2, v1
	v_add_f32_e32 v0, v1, v0
	v_mov_b32_e32 v242, v0
	v_mov_b32_e32 v243, v0
	s_nop 1
	v_permlane16_swap_b32_e32 v242, v243
	v_add_f32_e32 v0, v242, v243
	v_mov_b32_e32 v242, v0
	v_mov_b32_e32 v243, v0
	s_nop 1
	v_permlane32_swap_b32_e32 v242, v243
	s_and_saveexec_b64 s[8:9], s[38:39]
	s_cbranch_execz .LBB0_748
	s_waitcnt lgkmcnt(0)
	v_add_f32_e32 v0, v242, v243
	v_mul_f32_e32 v0, 0x4b800000, v0
	v_trunc_f32_e32 v0, v0
	v_mul_f32_e32 v1, 0x2f800000, v0
	v_floor_f32_e32 v1, v1
	v_fmac_f32_e32 v0, 0xcf800000, v1
	v_cvt_u32_f32_e32 v0, v0
	v_cvt_u32_f32_e32 v1, v1
	global_atomic_add_x2 v[134:135], v[0:1], off offset:1408

.LBB0_1041:
	v_lshl_add_u32 v212, s72, 8, v222
	v_ashrrev_i32_e32 v213, 31, v212
	v_lshl_or_b32 v88, s33, 8, v224
	v_lshlrev_b64 v[90:91], 12, v[212:213]
	v_lshl_add_u64 v[90:91], s[30:31], 0, v[90:91]
	v_ashrrev_i32_e32 v89, 31, v88
	v_lshl_add_u64 v[210:211], v[88:89], 1, v[90:91]
	global_load_dwordx4 v[228:231], v[210:211], off
	global_load_dwordx4 v[186:189], v[210:211], off offset:256
	v_add_co_u32_e32 v88, vcc, 0x10000, v210
	v_readlane_b32 s8, v237, 51
	s_nop 0
	v_addc_co_u32_e32 v89, vcc, 0, v211, vcc
	v_readlane_b32 s11, v237, 54
	global_load_dwordx4 v[182:185], v[88:89], off
	global_load_dwordx4 v[178:181], v[88:89], off offset:256
	v_add_co_u32_e32 v88, vcc, s11, v210
	s_mov_b32 s8, 0x80000
	s_nop 0
	v_addc_co_u32_e32 v89, vcc, 0, v211, vcc
	global_load_dwordx4 v[174:177], v[88:89], off
	global_load_dwordx4 v[170:173], v[88:89], off offset:256
	v_add_co_u32_e32 v88, vcc, 0x30000, v210
	v_and_b32_e32 v227, 64, v214
	s_nop 0
	v_addc_co_u32_e32 v89, vcc, 0, v211, vcc
	global_load_dwordx4 v[166:169], v[88:89], off
	global_load_dwordx4 v[162:165], v[88:89], off offset:256
	v_add_co_u32_e32 v88, vcc, s8, v210
	s_mov_b32 s8, 0xb0000
	s_nop 0
	v_addc_co_u32_e32 v89, vcc, 0, v211, vcc
	global_load_dwordx4 v[154:157], v[88:89], off
	global_load_dwordx4 v[146:149], v[88:89], off offset:256
	v_add_co_u32_e32 v88, vcc, 0x90000, v210
	v_xor_b32_e32 v226, 16, v214
	s_nop 0
	v_addc_co_u32_e32 v89, vcc, 0, v211, vcc
	global_load_dwordx4 v[138:141], v[88:89], off
	global_load_dwordx4 v[130:133], v[88:89], off offset:256
	v_add_co_u32_e32 v88, vcc, 0xa0000, v210
	v_add_u32_e32 v227, 64, v227
	s_nop 0
	v_addc_co_u32_e32 v89, vcc, 0, v211, vcc
	global_load_dwordx4 v[116:119], v[88:89], off
	global_load_dwordx4 v[104:107], v[88:89], off offset:256
	v_add_co_u32_e32 v88, vcc, s8, v210
	v_xor_b32_e32 v232, 32, v214
	s_nop 0
	v_addc_co_u32_e32 v89, vcc, 0, v211, vcc
	global_load_dwordx4 v[96:99], v[88:89], off
	s_nop 0
	global_load_dwordx4 v[88:91], v[88:89], off offset:256
	v_cmp_lt_i32_e32 vcc, v226, v227
	v_readlane_b32 s9, v237, 52
	v_readlane_b32 s10, v237, 53
	v_cndmask_b32_e32 v226, v214, v226, vcc
	v_cmp_lt_i32_e32 vcc, v232, v227
	v_lshlrev_b32_e32 v226, 2, v226
	s_waitcnt vmcnt(0)
	v_and_b32_e32 v233, 0xffff0000, v228
	v_cndmask_b32_e32 v227, v214, v232, vcc
	v_lshlrev_b32_e32 v232, 16, v228
	v_lshlrev_b32_e32 v228, 16, v229
	v_and_b32_e32 v229, 0xffff0000, v229
	v_pk_add_f32 v[160:161], v[160:161], v[228:229]
	v_lshlrev_b32_e32 v228, 16, v230
	v_and_b32_e32 v229, 0xffff0000, v230
	v_pk_add_f32 v[228:229], v[150:151], v[228:229]
	v_lshlrev_b32_e32 v150, 16, v231
	v_and_b32_e32 v151, 0xffff0000, v231
	v_pk_add_f32 v[158:159], v[158:159], v[232:233]
	v_pk_add_f32 v[230:231], v[152:153], v[150:151]
	v_cvt_pk_bf16_f32 v150, v158, v159
	v_cvt_pk_bf16_f32 v151, v160, v161
	v_cvt_pk_bf16_f32 v152, v228, v229
	v_cvt_pk_bf16_f32 v153, v230, v231
	global_store_dwordx4 v[210:211], v[150:153], off sc1
	v_lshlrev_b32_e32 v227, 2, v227
	s_nop 0
	v_pk_mul_f32 v[150:151], v[158:159], v[158:159]
	v_pk_mul_f32 v[158:159], v[228:229], v[228:229]
	v_lshlrev_b32_e32 v228, 16, v186
	v_and_b32_e32 v229, 0xffff0000, v186
	v_lshlrev_b32_e32 v186, 16, v187
	v_and_b32_e32 v187, 0xffff0000, v187
	v_pk_add_f32 v[144:145], v[144:145], v[186:187]
	v_lshlrev_b32_e32 v186, 16, v188
	v_and_b32_e32 v187, 0xffff0000, v188
	v_pk_add_f32 v[186:187], v[134:135], v[186:187]
	v_lshlrev_b32_e32 v134, 16, v189
	v_and_b32_e32 v135, 0xffff0000, v189
	v_pk_add_f32 v[142:143], v[142:143], v[228:229]
	v_pk_add_f32 v[188:189], v[136:137], v[134:135]
	v_cvt_pk_bf16_f32 v134, v142, v143
	v_cvt_pk_bf16_f32 v135, v144, v145
	v_cvt_pk_bf16_f32 v136, v186, v187
	v_cvt_pk_bf16_f32 v137, v188, v189
	global_store_dwordx4 v[210:211], v[134:137], off offset:256 sc1
	v_pk_mul_f32 v[152:153], v[160:161], v[160:161]
	v_pk_mul_f32 v[160:161], v[230:231], v[230:231]
	v_pk_mul_f32 v[134:135], v[142:143], v[142:143]
	v_pk_mul_f32 v[136:137], v[144:145], v[144:145]
	v_add_f32_e32 v134, v134, v135
	v_add_f32_e32 v136, v136, v137
	v_pk_mul_f32 v[142:143], v[186:187], v[186:187]
	v_pk_mul_f32 v[144:145], v[188:189], v[188:189]
	v_add_f32_e32 v134, v134, v136
	v_add_f32_e32 v135, v160, v161
	v_add_f32_e32 v136, v158, v159
	v_add_f32_e32 v144, v144, v145
	v_add_f32_e32 v142, v142, v143
	v_add_f32_e32 v135, v136, v135
	v_add_f32_e32 v136, v152, v153
	v_add_f32_e32 v137, v150, v151
	v_add_f32_e32 v142, v142, v144
	v_add_f32_e32 v136, v137, v136
	v_add_f32_e32 v134, v134, v142
	v_add_f32_e32 v135, v136, v135
	v_add_f32_e32 v134, v135, v134
	v_mov_b32_e32 v242, v134
	v_mov_b32_e32 v243, v134
	s_nop 1
	v_permlane16_swap_b32_e32 v242, v243
	v_add_f32_e32 v136, v242, v243
	v_mov_b32_e32 v242, v136
	v_mov_b32_e32 v243, v136
	s_nop 1
	v_permlane32_swap_b32_e32 v242, v243
	v_lshl_add_u64 v[134:135], v[212:213], 3, s[38:39]
	s_and_saveexec_b64 s[8:9], s[40:41]
	s_cbranch_execz .LBB0_1043
	s_waitcnt lgkmcnt(0)
	v_add_f32_e32 v136, v242, v243
	v_mul_f32_e32 v136, 0x4b800000, v136
	v_trunc_f32_e32 v136, v136
	v_mul_f32_e32 v137, 0x2f800000, v136
	v_floor_f32_e32 v137, v137
	v_fmac_f32_e32 v136, 0xcf800000, v137
	v_cvt_u32_f32_e32 v136, v136
	v_cvt_u32_f32_e32 v137, v137
	global_atomic_add_x2 v[134:135], v[136:137], off
.LBB0_1043:
	s_or_b64 exec, exec, s[8:9]
	v_lshlrev_b32_e32 v144, 16, v182
	v_and_b32_e32 v145, 0xffff0000, v182
	v_pk_add_f32 v[124:125], v[124:125], v[144:145]
	v_lshlrev_b32_e32 v144, 16, v183
	v_and_b32_e32 v145, 0xffff0000, v183
	v_pk_add_f32 v[126:127], v[126:127], v[144:145]
	v_lshlrev_b32_e32 v144, 16, v184
	v_and_b32_e32 v145, 0xffff0000, v184
	v_pk_add_f32 v[144:145], v[120:121], v[144:145]
	v_lshlrev_b32_e32 v120, 16, v185
	v_and_b32_e32 v121, 0xffff0000, v185
	s_mov_b64 s[8:9], 0x10000
	v_pk_add_f32 v[150:151], v[122:123], v[120:121]
	s_waitcnt lgkmcnt(0)
	v_lshl_add_u64 v[136:137], v[210:211], 0, s[8:9]
	v_cvt_pk_bf16_f32 v120, v124, v125
	v_cvt_pk_bf16_f32 v121, v126, v127
	v_cvt_pk_bf16_f32 v122, v144, v145
	v_cvt_pk_bf16_f32 v123, v150, v151
	global_store_dwordx4 v[136:137], v[120:123], off sc1
	v_lshlrev_b32_e32 v136, 16, v178
	v_and_b32_e32 v137, 0xffff0000, v178
	v_pk_add_f32 v[112:113], v[112:113], v[136:137]
	v_lshlrev_b32_e32 v136, 16, v179
	v_and_b32_e32 v137, 0xffff0000, v179
	v_pk_add_f32 v[114:115], v[114:115], v[136:137]
	v_lshlrev_b32_e32 v136, 16, v180
	v_and_b32_e32 v137, 0xffff0000, v180
	v_pk_add_f32 v[136:137], v[108:109], v[136:137]
	v_lshlrev_b32_e32 v108, 16, v181
	v_and_b32_e32 v109, 0xffff0000, v181
	s_mov_b64 s[8:9], 0x10100
	v_pk_mul_f32 v[120:121], v[124:125], v[124:125]
	v_pk_mul_f32 v[124:125], v[144:145], v[144:145]
	v_pk_add_f32 v[144:145], v[110:111], v[108:109]
	v_lshl_add_u64 v[142:143], v[210:211], 0, s[8:9]
	v_cvt_pk_bf16_f32 v108, v112, v113
	v_cvt_pk_bf16_f32 v109, v114, v115
	v_cvt_pk_bf16_f32 v110, v136, v137
	v_cvt_pk_bf16_f32 v111, v144, v145
	global_store_dwordx4 v[142:143], v[108:111], off sc1
	v_pk_mul_f32 v[122:123], v[126:127], v[126:127]
	v_pk_mul_f32 v[126:127], v[150:151], v[150:151]
	v_pk_mul_f32 v[108:109], v[112:113], v[112:113]
	v_pk_mul_f32 v[110:111], v[114:115], v[114:115]
	v_add_f32_e32 v108, v108, v109
	v_add_f32_e32 v110, v110, v111
	v_pk_mul_f32 v[112:113], v[136:137], v[136:137]
	v_pk_mul_f32 v[114:115], v[144:145], v[144:145]
	v_add_f32_e32 v108, v108, v110
	v_add_f32_e32 v109, v126, v127
	v_add_f32_e32 v110, v124, v125
	v_add_f32_e32 v114, v114, v115
	v_add_f32_e32 v112, v112, v113
	v_add_f32_e32 v109, v110, v109
	v_add_f32_e32 v110, v122, v123
	v_add_f32_e32 v111, v120, v121
	v_add_f32_e32 v112, v112, v114
	v_add_f32_e32 v110, v111, v110
	v_add_f32_e32 v108, v108, v112
	v_add_f32_e32 v109, v110, v109
	v_add_f32_e32 v108, v109, v108
	v_mov_b32_e32 v242, v108
	v_mov_b32_e32 v243, v108
	s_nop 1
	v_permlane16_swap_b32_e32 v242, v243
	v_add_f32_e32 v108, v242, v243
	v_mov_b32_e32 v242, v108
	v_mov_b32_e32 v243, v108
	s_nop 1
	v_permlane32_swap_b32_e32 v242, v243
	s_and_saveexec_b64 s[8:9], s[40:41]
	s_cbranch_execz .LBB0_1045
	s_waitcnt lgkmcnt(0)
	v_add_f32_e32 v108, v242, v243
	v_mul_f32_e32 v108, 0x4b800000, v108
	v_trunc_f32_e32 v108, v108
	v_mul_f32_e32 v109, 0x2f800000, v108
	v_floor_f32_e32 v109, v109
	v_fmac_f32_e32 v108, 0xcf800000, v109
	v_cvt_u32_f32_e32 v108, v108
	v_cvt_u32_f32_e32 v109, v109
	global_atomic_add_x2 v[134:135], v[108:109], off offset:128
.LBB0_1045:
	s_or_b64 exec, exec, s[8:9]
	v_lshlrev_b32_e32 v112, 16, v174
	v_and_b32_e32 v113, 0xffff0000, v174
	v_pk_add_f32 v[100:101], v[100:101], v[112:113]
	v_lshlrev_b32_e32 v112, 16, v175
	v_and_b32_e32 v113, 0xffff0000, v175
	v_pk_add_f32 v[102:103], v[102:103], v[112:113]
	v_lshlrev_b32_e32 v112, 16, v176
	v_and_b32_e32 v113, 0xffff0000, v176
	v_pk_add_f32 v[112:113], v[92:93], v[112:113]
	v_lshlrev_b32_e32 v92, 16, v177
	v_and_b32_e32 v93, 0xffff0000, v177
	s_mov_b64 s[8:9], 0x20000
	v_pk_add_f32 v[114:115], v[94:95], v[92:93]
	s_waitcnt lgkmcnt(0)
	v_lshl_add_u64 v[108:109], v[210:211], 0, s[8:9]
	v_cvt_pk_bf16_f32 v92, v100, v101
	v_cvt_pk_bf16_f32 v93, v102, v103
	v_cvt_pk_bf16_f32 v94, v112, v113
	v_cvt_pk_bf16_f32 v95, v114, v115
	global_store_dwordx4 v[108:109], v[92:95], off sc1
	v_lshlrev_b32_e32 v108, 16, v170
	v_and_b32_e32 v109, 0xffff0000, v170
	v_pk_add_f32 v[84:85], v[84:85], v[108:109]
	v_lshlrev_b32_e32 v108, 16, v171
	v_and_b32_e32 v109, 0xffff0000, v171
	v_pk_add_f32 v[86:87], v[86:87], v[108:109]
	v_lshlrev_b32_e32 v108, 16, v172
	v_and_b32_e32 v109, 0xffff0000, v172
	v_pk_add_f32 v[108:109], v[80:81], v[108:109]
	v_lshlrev_b32_e32 v80, 16, v173
	v_and_b32_e32 v81, 0xffff0000, v173
	s_mov_b64 s[8:9], 0x20100
	v_pk_mul_f32 v[92:93], v[100:101], v[100:101]
	v_pk_mul_f32 v[100:101], v[112:113], v[112:113]
	v_pk_add_f32 v[112:113], v[82:83], v[80:81]
	v_lshl_add_u64 v[110:111], v[210:211], 0, s[8:9]
	v_cvt_pk_bf16_f32 v80, v84, v85
	v_cvt_pk_bf16_f32 v81, v86, v87
	v_cvt_pk_bf16_f32 v82, v108, v109
	v_cvt_pk_bf16_f32 v83, v112, v113
	global_store_dwordx4 v[110:111], v[80:83], off sc1
	v_pk_mul_f32 v[94:95], v[102:103], v[102:103]
	v_pk_mul_f32 v[102:103], v[114:115], v[114:115]
	v_pk_mul_f32 v[80:81], v[84:85], v[84:85]
	v_pk_mul_f32 v[82:83], v[86:87], v[86:87]
	v_add_f32_e32 v80, v80, v81
	v_add_f32_e32 v82, v82, v83
	v_pk_mul_f32 v[84:85], v[108:109], v[108:109]
	v_pk_mul_f32 v[86:87], v[112:113], v[112:113]
	v_add_f32_e32 v80, v80, v82
	v_add_f32_e32 v81, v102, v103
	v_add_f32_e32 v82, v100, v101
	v_add_f32_e32 v86, v86, v87
	v_add_f32_e32 v84, v84, v85
	v_add_f32_e32 v81, v82, v81
	v_add_f32_e32 v82, v94, v95
	v_add_f32_e32 v83, v92, v93
	v_add_f32_e32 v84, v84, v86
	v_add_f32_e32 v82, v83, v82
	v_add_f32_e32 v80, v80, v84
	v_add_f32_e32 v81, v82, v81
	v_add_f32_e32 v80, v81, v80
	v_mov_b32_e32 v242, v80
	v_mov_b32_e32 v243, v80
	s_nop 1
	v_permlane16_swap_b32_e32 v242, v243
	v_add_f32_e32 v80, v242, v243
	v_mov_b32_e32 v242, v80
	v_mov_b32_e32 v243, v80
	s_nop 1
	v_permlane32_swap_b32_e32 v242, v243
	s_and_saveexec_b64 s[8:9], s[40:41]
	s_mov_b64 s[28:29], s[34:35]
	s_cbranch_execz .LBB0_1047
	s_waitcnt lgkmcnt(0)
	v_add_f32_e32 v80, v242, v243
	v_mul_f32_e32 v80, 0x4b800000, v80
	v_trunc_f32_e32 v80, v80
	v_mul_f32_e32 v81, 0x2f800000, v80
	v_floor_f32_e32 v81, v81
	v_fmac_f32_e32 v80, 0xcf800000, v81
	v_cvt_u32_f32_e32 v80, v80
	v_cvt_u32_f32_e32 v81, v81
	global_atomic_add_x2 v[134:135], v[80:81], off offset:256
.LBB0_1047:
	s_or_b64 exec, exec, s[8:9]
	v_lshlrev_b32_e32 v84, 16, v166
	v_and_b32_e32 v85, 0xffff0000, v166
	v_pk_add_f32 v[76:77], v[76:77], v[84:85]
	v_lshlrev_b32_e32 v84, 16, v167
	v_and_b32_e32 v85, 0xffff0000, v167
	v_pk_add_f32 v[78:79], v[78:79], v[84:85]
	v_lshlrev_b32_e32 v84, 16, v168
	v_and_b32_e32 v85, 0xffff0000, v168
	v_pk_add_f32 v[84:85], v[72:73], v[84:85]
	v_lshlrev_b32_e32 v72, 16, v169
	v_and_b32_e32 v73, 0xffff0000, v169
	s_mov_b64 s[8:9], 0x30000
	v_pk_add_f32 v[86:87], v[74:75], v[72:73]
	s_waitcnt lgkmcnt(0)
	v_lshl_add_u64 v[80:81], v[210:211], 0, s[8:9]
	v_cvt_pk_bf16_f32 v72, v76, v77
	v_cvt_pk_bf16_f32 v73, v78, v79
	v_cvt_pk_bf16_f32 v74, v84, v85
	v_cvt_pk_bf16_f32 v75, v86, v87
	global_store_dwordx4 v[80:81], v[72:75], off sc1
	v_lshlrev_b32_e32 v80, 16, v162
	v_and_b32_e32 v81, 0xffff0000, v162
	v_pk_add_f32 v[68:69], v[68:69], v[80:81]
	v_lshlrev_b32_e32 v80, 16, v163
	v_and_b32_e32 v81, 0xffff0000, v163
	v_pk_add_f32 v[70:71], v[70:71], v[80:81]
	v_lshlrev_b32_e32 v80, 16, v164
	v_and_b32_e32 v81, 0xffff0000, v164
	v_pk_add_f32 v[80:81], v[64:65], v[80:81]
	v_lshlrev_b32_e32 v64, 16, v165
	v_and_b32_e32 v65, 0xffff0000, v165
	s_mov_b64 s[8:9], 0x30100
	v_pk_mul_f32 v[72:73], v[76:77], v[76:77]
	v_pk_mul_f32 v[76:77], v[84:85], v[84:85]
	v_pk_add_f32 v[84:85], v[66:67], v[64:65]
	v_lshl_add_u64 v[82:83], v[210:211], 0, s[8:9]
	v_cvt_pk_bf16_f32 v64, v68, v69
	v_cvt_pk_bf16_f32 v65, v70, v71
	v_cvt_pk_bf16_f32 v66, v80, v81
	v_cvt_pk_bf16_f32 v67, v84, v85
	global_store_dwordx4 v[82:83], v[64:67], off sc1
	v_pk_mul_f32 v[74:75], v[78:79], v[78:79]
	v_pk_mul_f32 v[78:79], v[86:87], v[86:87]
	v_pk_mul_f32 v[64:65], v[68:69], v[68:69]
	v_pk_mul_f32 v[66:67], v[70:71], v[70:71]
	v_add_f32_e32 v64, v64, v65
	v_add_f32_e32 v66, v66, v67
	v_pk_mul_f32 v[68:69], v[80:81], v[80:81]
	v_pk_mul_f32 v[70:71], v[84:85], v[84:85]
	v_add_f32_e32 v64, v64, v66
	v_add_f32_e32 v65, v78, v79
	v_add_f32_e32 v66, v76, v77
	v_add_f32_e32 v70, v70, v71
	v_add_f32_e32 v68, v68, v69
	v_add_f32_e32 v65, v66, v65
	v_add_f32_e32 v66, v74, v75
	v_add_f32_e32 v67, v72, v73
	v_add_f32_e32 v68, v68, v70
	v_add_f32_e32 v66, v67, v66
	v_add_f32_e32 v64, v64, v68
	v_add_f32_e32 v65, v66, v65
	v_add_f32_e32 v64, v65, v64
	v_mov_b32_e32 v242, v64
	v_mov_b32_e32 v243, v64
	s_nop 1
	v_permlane16_swap_b32_e32 v242, v243
	v_add_f32_e32 v64, v242, v243
	v_mov_b32_e32 v242, v64
	v_mov_b32_e32 v243, v64
	s_nop 1
	v_permlane32_swap_b32_e32 v242, v243
	s_and_saveexec_b64 s[8:9], s[40:41]
	s_cbranch_execz .LBB0_1049
	s_waitcnt lgkmcnt(0)
	v_add_f32_e32 v64, v242, v243
	v_mul_f32_e32 v64, 0x4b800000, v64
	v_trunc_f32_e32 v64, v64
	v_mul_f32_e32 v65, 0x2f800000, v64
	v_floor_f32_e32 v65, v65
	v_fmac_f32_e32 v64, 0xcf800000, v65
	v_cvt_u32_f32_e32 v64, v64
	v_cvt_u32_f32_e32 v65, v65
	global_atomic_add_x2 v[134:135], v[64:65], off offset:384
.LBB0_1049:
	s_or_b64 exec, exec, s[8:9]
	v_lshlrev_b32_e32 v68, 16, v154
	v_and_b32_e32 v69, 0xffff0000, v154
	v_pk_add_f32 v[60:61], v[60:61], v[68:69]
	v_lshlrev_b32_e32 v68, 16, v155
	v_and_b32_e32 v69, 0xffff0000, v155
	v_pk_add_f32 v[62:63], v[62:63], v[68:69]
	v_lshlrev_b32_e32 v68, 16, v156
	v_and_b32_e32 v69, 0xffff0000, v156
	v_pk_add_f32 v[68:69], v[56:57], v[68:69]
	v_lshlrev_b32_e32 v56, 16, v157
	v_and_b32_e32 v57, 0xffff0000, v157
	s_mov_b64 s[8:9], 0x80000
	v_pk_add_f32 v[70:71], v[58:59], v[56:57]
	s_waitcnt lgkmcnt(0)
	v_lshl_add_u64 v[64:65], v[210:211], 0, s[8:9]
	v_cvt_pk_bf16_f32 v56, v60, v61
	v_cvt_pk_bf16_f32 v57, v62, v63
	v_cvt_pk_bf16_f32 v58, v68, v69
	v_cvt_pk_bf16_f32 v59, v70, v71
	global_store_dwordx4 v[64:65], v[56:59], off sc1
	v_lshlrev_b32_e32 v64, 16, v146
	v_and_b32_e32 v65, 0xffff0000, v146
	v_pk_add_f32 v[52:53], v[52:53], v[64:65]
	v_lshlrev_b32_e32 v64, 16, v147
	v_and_b32_e32 v65, 0xffff0000, v147
	v_pk_add_f32 v[54:55], v[54:55], v[64:65]
	v_lshlrev_b32_e32 v64, 16, v148
	v_and_b32_e32 v65, 0xffff0000, v148
	v_pk_add_f32 v[64:65], v[48:49], v[64:65]
	v_lshlrev_b32_e32 v48, 16, v149
	v_and_b32_e32 v49, 0xffff0000, v149
	s_mov_b64 s[8:9], 0x80100
	v_pk_mul_f32 v[56:57], v[60:61], v[60:61]
	v_pk_mul_f32 v[60:61], v[68:69], v[68:69]
	v_pk_add_f32 v[68:69], v[50:51], v[48:49]
	v_lshl_add_u64 v[66:67], v[210:211], 0, s[8:9]
	v_cvt_pk_bf16_f32 v48, v52, v53
	v_cvt_pk_bf16_f32 v49, v54, v55
	v_cvt_pk_bf16_f32 v50, v64, v65
	v_cvt_pk_bf16_f32 v51, v68, v69
	global_store_dwordx4 v[66:67], v[48:51], off sc1
	v_pk_mul_f32 v[58:59], v[62:63], v[62:63]
	v_pk_mul_f32 v[62:63], v[70:71], v[70:71]
	v_pk_mul_f32 v[48:49], v[52:53], v[52:53]
	v_pk_mul_f32 v[50:51], v[54:55], v[54:55]
	v_add_f32_e32 v48, v48, v49
	v_add_f32_e32 v50, v50, v51
	v_pk_mul_f32 v[52:53], v[64:65], v[64:65]
	v_pk_mul_f32 v[54:55], v[68:69], v[68:69]
	v_add_f32_e32 v48, v48, v50
	v_add_f32_e32 v49, v62, v63
	v_add_f32_e32 v50, v60, v61
	v_add_f32_e32 v54, v54, v55
	v_add_f32_e32 v52, v52, v53
	v_add_f32_e32 v49, v50, v49
	v_add_f32_e32 v50, v58, v59
	v_add_f32_e32 v51, v56, v57
	v_add_f32_e32 v52, v52, v54
	v_add_f32_e32 v50, v51, v50
	v_add_f32_e32 v48, v48, v52
	v_add_f32_e32 v49, v50, v49
	v_add_f32_e32 v48, v49, v48
	v_mov_b32_e32 v242, v48
	v_mov_b32_e32 v243, v48
	s_nop 1
	v_permlane16_swap_b32_e32 v242, v243
	v_add_f32_e32 v48, v242, v243
	v_mov_b32_e32 v242, v48
	v_mov_b32_e32 v243, v48
	s_nop 1
	v_permlane32_swap_b32_e32 v242, v243
	s_and_saveexec_b64 s[8:9], s[40:41]
	s_cbranch_execz .LBB0_1051
	s_waitcnt lgkmcnt(0)
	v_add_f32_e32 v48, v242, v243
	v_mul_f32_e32 v48, 0x4b800000, v48
	v_trunc_f32_e32 v48, v48
	v_mul_f32_e32 v49, 0x2f800000, v48
	v_floor_f32_e32 v49, v49
	v_fmac_f32_e32 v48, 0xcf800000, v49
	v_cvt_u32_f32_e32 v48, v48
	v_cvt_u32_f32_e32 v49, v49
	global_atomic_add_x2 v[134:135], v[48:49], off offset:1024
.LBB0_1051:
	s_or_b64 exec, exec, s[8:9]
	v_lshlrev_b32_e32 v52, 16, v138
	v_and_b32_e32 v53, 0xffff0000, v138
	v_pk_add_f32 v[44:45], v[44:45], v[52:53]
	v_lshlrev_b32_e32 v52, 16, v139
	v_and_b32_e32 v53, 0xffff0000, v139
	v_pk_add_f32 v[46:47], v[46:47], v[52:53]
	v_lshlrev_b32_e32 v52, 16, v140
	v_and_b32_e32 v53, 0xffff0000, v140
	v_pk_add_f32 v[52:53], v[40:41], v[52:53]
	v_lshlrev_b32_e32 v40, 16, v141
	v_and_b32_e32 v41, 0xffff0000, v141
	s_mov_b64 s[8:9], 0x90000
	v_pk_add_f32 v[54:55], v[42:43], v[40:41]
	s_waitcnt lgkmcnt(0)
	v_lshl_add_u64 v[48:49], v[210:211], 0, s[8:9]
	v_cvt_pk_bf16_f32 v40, v44, v45
	v_cvt_pk_bf16_f32 v41, v46, v47
	v_cvt_pk_bf16_f32 v42, v52, v53
	v_cvt_pk_bf16_f32 v43, v54, v55
	global_store_dwordx4 v[48:49], v[40:43], off sc1
	v_lshlrev_b32_e32 v48, 16, v130
	v_and_b32_e32 v49, 0xffff0000, v130
	v_pk_add_f32 v[36:37], v[36:37], v[48:49]
	v_lshlrev_b32_e32 v48, 16, v131
	v_and_b32_e32 v49, 0xffff0000, v131
	v_pk_add_f32 v[38:39], v[38:39], v[48:49]
	v_lshlrev_b32_e32 v48, 16, v132
	v_and_b32_e32 v49, 0xffff0000, v132
	v_pk_add_f32 v[48:49], v[32:33], v[48:49]
	v_lshlrev_b32_e32 v32, 16, v133
	v_and_b32_e32 v33, 0xffff0000, v133
	s_mov_b64 s[8:9], 0x90100
	v_pk_mul_f32 v[40:41], v[44:45], v[44:45]
	v_pk_mul_f32 v[44:45], v[52:53], v[52:53]
	v_pk_add_f32 v[52:53], v[34:35], v[32:33]
	v_lshl_add_u64 v[50:51], v[210:211], 0, s[8:9]
	v_cvt_pk_bf16_f32 v32, v36, v37
	v_cvt_pk_bf16_f32 v33, v38, v39
	v_cvt_pk_bf16_f32 v34, v48, v49
	v_cvt_pk_bf16_f32 v35, v52, v53
	global_store_dwordx4 v[50:51], v[32:35], off sc1
	v_pk_mul_f32 v[42:43], v[46:47], v[46:47]
	v_pk_mul_f32 v[46:47], v[54:55], v[54:55]
	v_pk_mul_f32 v[32:33], v[36:37], v[36:37]
	v_pk_mul_f32 v[34:35], v[38:39], v[38:39]
	v_add_f32_e32 v32, v32, v33
	v_add_f32_e32 v34, v34, v35
	v_pk_mul_f32 v[36:37], v[48:49], v[48:49]
	v_pk_mul_f32 v[38:39], v[52:53], v[52:53]
	v_add_f32_e32 v32, v32, v34
	v_add_f32_e32 v33, v46, v47
	v_add_f32_e32 v34, v44, v45
	v_add_f32_e32 v38, v38, v39
	v_add_f32_e32 v36, v36, v37
	v_add_f32_e32 v33, v34, v33
	v_add_f32_e32 v34, v42, v43
	v_add_f32_e32 v35, v40, v41
	v_add_f32_e32 v36, v36, v38
	v_add_f32_e32 v34, v35, v34
	v_add_f32_e32 v32, v32, v36
	v_add_f32_e32 v33, v34, v33
	v_add_f32_e32 v32, v33, v32
	v_mov_b32_e32 v242, v32
	v_mov_b32_e32 v243, v32
	s_nop 1
	v_permlane16_swap_b32_e32 v242, v243
	v_add_f32_e32 v32, v242, v243
	v_mov_b32_e32 v242, v32
	v_mov_b32_e32 v243, v32
	s_nop 1
	v_permlane32_swap_b32_e32 v242, v243
	s_and_saveexec_b64 s[8:9], s[40:41]
	s_cbranch_execz .LBB0_1053
	s_waitcnt lgkmcnt(0)
	v_add_f32_e32 v32, v242, v243
	v_mul_f32_e32 v32, 0x4b800000, v32
	v_trunc_f32_e32 v32, v32
	v_mul_f32_e32 v33, 0x2f800000, v32
	v_floor_f32_e32 v33, v33
	v_fmac_f32_e32 v32, 0xcf800000, v33
	v_cvt_u32_f32_e32 v32, v32
	v_cvt_u32_f32_e32 v33, v33
	global_atomic_add_x2 v[134:135], v[32:33], off offset:1152
.LBB0_1053:
	s_or_b64 exec, exec, s[8:9]
	v_lshlrev_b32_e32 v36, 16, v116
	v_and_b32_e32 v37, 0xffff0000, v116
	v_pk_add_f32 v[28:29], v[28:29], v[36:37]
	v_lshlrev_b32_e32 v36, 16, v117
	v_and_b32_e32 v37, 0xffff0000, v117
	v_pk_add_f32 v[30:31], v[30:31], v[36:37]
	v_lshlrev_b32_e32 v36, 16, v118
	v_and_b32_e32 v37, 0xffff0000, v118
	v_pk_add_f32 v[36:37], v[24:25], v[36:37]
	v_lshlrev_b32_e32 v24, 16, v119
	v_and_b32_e32 v25, 0xffff0000, v119
	s_mov_b64 s[8:9], 0xa0000
	v_pk_add_f32 v[38:39], v[26:27], v[24:25]
	s_waitcnt lgkmcnt(0)
	v_lshl_add_u64 v[32:33], v[210:211], 0, s[8:9]
	v_cvt_pk_bf16_f32 v24, v28, v29
	v_cvt_pk_bf16_f32 v25, v30, v31
	v_cvt_pk_bf16_f32 v26, v36, v37
	v_cvt_pk_bf16_f32 v27, v38, v39
	global_store_dwordx4 v[32:33], v[24:27], off sc1
	v_lshlrev_b32_e32 v32, 16, v104
	v_and_b32_e32 v33, 0xffff0000, v104
	v_pk_add_f32 v[20:21], v[20:21], v[32:33]
	v_lshlrev_b32_e32 v32, 16, v105
	v_and_b32_e32 v33, 0xffff0000, v105
	v_pk_add_f32 v[22:23], v[22:23], v[32:33]
	v_lshlrev_b32_e32 v32, 16, v106
	v_and_b32_e32 v33, 0xffff0000, v106
	v_pk_add_f32 v[32:33], v[16:17], v[32:33]
	v_lshlrev_b32_e32 v16, 16, v107
	v_and_b32_e32 v17, 0xffff0000, v107
	s_mov_b64 s[8:9], 0xa0100
	v_pk_mul_f32 v[24:25], v[28:29], v[28:29]
	v_pk_mul_f32 v[28:29], v[36:37], v[36:37]
	v_pk_add_f32 v[36:37], v[18:19], v[16:17]
	v_lshl_add_u64 v[34:35], v[210:211], 0, s[8:9]
	v_cvt_pk_bf16_f32 v16, v20, v21
	v_cvt_pk_bf16_f32 v17, v22, v23
	v_cvt_pk_bf16_f32 v18, v32, v33
	v_cvt_pk_bf16_f32 v19, v36, v37
	global_store_dwordx4 v[34:35], v[16:19], off sc1
	v_pk_mul_f32 v[26:27], v[30:31], v[30:31]
	v_pk_mul_f32 v[30:31], v[38:39], v[38:39]
	v_pk_mul_f32 v[16:17], v[20:21], v[20:21]
	v_pk_mul_f32 v[18:19], v[22:23], v[22:23]
	v_add_f32_e32 v16, v16, v17
	v_add_f32_e32 v18, v18, v19
	v_pk_mul_f32 v[20:21], v[32:33], v[32:33]
	v_pk_mul_f32 v[22:23], v[36:37], v[36:37]
	v_add_f32_e32 v16, v16, v18
	v_add_f32_e32 v17, v30, v31
	v_add_f32_e32 v18, v28, v29
	v_add_f32_e32 v22, v22, v23
	v_add_f32_e32 v20, v20, v21
	v_add_f32_e32 v17, v18, v17
	v_add_f32_e32 v18, v26, v27
	v_add_f32_e32 v19, v24, v25
	v_add_f32_e32 v20, v20, v22
	v_add_f32_e32 v18, v19, v18
	v_add_f32_e32 v16, v16, v20
	v_add_f32_e32 v17, v18, v17
	v_add_f32_e32 v16, v17, v16
	v_mov_b32_e32 v242, v16
	v_mov_b32_e32 v243, v16
	s_nop 1
	v_permlane16_swap_b32_e32 v242, v243
	v_add_f32_e32 v16, v242, v243
	v_mov_b32_e32 v242, v16
	v_mov_b32_e32 v243, v16
	s_nop 1
	v_permlane32_swap_b32_e32 v242, v243
	s_and_saveexec_b64 s[8:9], s[40:41]
	s_cbranch_execz .LBB0_1055
	s_waitcnt lgkmcnt(0)
	v_add_f32_e32 v16, v242, v243
	v_mul_f32_e32 v16, 0x4b800000, v16
	v_trunc_f32_e32 v16, v16
	v_mul_f32_e32 v17, 0x2f800000, v16
	v_floor_f32_e32 v17, v17
	v_fmac_f32_e32 v16, 0xcf800000, v17
	v_cvt_u32_f32_e32 v16, v16
	v_cvt_u32_f32_e32 v17, v17
	global_atomic_add_x2 v[134:135], v[16:17], off offset:1280
.LBB0_1055:
	s_or_b64 exec, exec, s[8:9]
	v_lshlrev_b32_e32 v20, 16, v96
	v_and_b32_e32 v21, 0xffff0000, v96
	v_pk_add_f32 v[12:13], v[12:13], v[20:21]
	v_lshlrev_b32_e32 v20, 16, v97
	v_and_b32_e32 v21, 0xffff0000, v97
	v_pk_add_f32 v[14:15], v[14:15], v[20:21]
	v_lshlrev_b32_e32 v20, 16, v98
	v_and_b32_e32 v21, 0xffff0000, v98
	v_pk_add_f32 v[20:21], v[8:9], v[20:21]
	v_lshlrev_b32_e32 v8, 16, v99
	v_and_b32_e32 v9, 0xffff0000, v99
	s_mov_b64 s[8:9], 0xb0000
	v_pk_add_f32 v[22:23], v[10:11], v[8:9]
	s_waitcnt lgkmcnt(0)
	v_lshl_add_u64 v[16:17], v[210:211], 0, s[8:9]
	v_cvt_pk_bf16_f32 v8, v12, v13
	v_cvt_pk_bf16_f32 v9, v14, v15
	v_cvt_pk_bf16_f32 v10, v20, v21
	v_cvt_pk_bf16_f32 v11, v22, v23
	global_store_dwordx4 v[16:17], v[8:11], off sc1
	v_lshlrev_b32_e32 v16, 16, v88
	v_and_b32_e32 v17, 0xffff0000, v88
	v_pk_add_f32 v[4:5], v[4:5], v[16:17]
	v_lshlrev_b32_e32 v16, 16, v89
	v_and_b32_e32 v17, 0xffff0000, v89
	v_pk_add_f32 v[6:7], v[6:7], v[16:17]
	v_lshlrev_b32_e32 v16, 16, v90
	v_and_b32_e32 v17, 0xffff0000, v90
	v_pk_add_f32 v[16:17], v[0:1], v[16:17]
	v_lshlrev_b32_e32 v0, 16, v91
	v_and_b32_e32 v1, 0xffff0000, v91
	s_mov_b64 s[8:9], 0xb0100
	v_pk_mul_f32 v[8:9], v[12:13], v[12:13]
	v_pk_mul_f32 v[12:13], v[20:21], v[20:21]
	v_pk_add_f32 v[20:21], v[2:3], v[0:1]
	v_lshl_add_u64 v[18:19], v[210:211], 0, s[8:9]
	v_cvt_pk_bf16_f32 v0, v4, v5
	v_cvt_pk_bf16_f32 v1, v6, v7
	v_cvt_pk_bf16_f32 v2, v16, v17
	v_cvt_pk_bf16_f32 v3, v20, v21
	global_store_dwordx4 v[18:19], v[0:3], off sc1
	v_pk_mul_f32 v[10:11], v[14:15], v[14:15]
	v_pk_mul_f32 v[14:15], v[22:23], v[22:23]
	v_pk_mul_f32 v[0:1], v[4:5], v[4:5]
	v_pk_mul_f32 v[2:3], v[6:7], v[6:7]
	v_add_f32_e32 v0, v0, v1
	v_add_f32_e32 v2, v2, v3
	v_pk_mul_f32 v[4:5], v[16:17], v[16:17]
	v_pk_mul_f32 v[6:7], v[20:21], v[20:21]
	v_add_f32_e32 v0, v0, v2
	v_add_f32_e32 v1, v14, v15
	v_add_f32_e32 v2, v12, v13
	v_add_f32_e32 v6, v6, v7
	v_add_f32_e32 v4, v4, v5
	v_add_f32_e32 v1, v2, v1
	v_add_f32_e32 v2, v10, v11
	v_add_f32_e32 v3, v8, v9
	v_add_f32_e32 v4, v4, v6
	v_add_f32_e32 v2, v3, v2
	v_add_f32_e32 v0, v0, v4
	v_add_f32_e32 v1, v2, v1
	v_add_f32_e32 v0, v1, v0
	v_mov_b32_e32 v242, v0
	v_mov_b32_e32 v243, v0
	s_nop 1
	v_permlane16_swap_b32_e32 v242, v243
	v_add_f32_e32 v0, v242, v243
	v_mov_b32_e32 v242, v0
	v_mov_b32_e32 v243, v0
	s_nop 1
	v_permlane32_swap_b32_e32 v242, v243
	s_and_saveexec_b64 s[8:9], s[40:41]
	s_cbranch_execz .LBB0_1057
	s_waitcnt lgkmcnt(0)
	v_add_f32_e32 v0, v242, v243
	v_mul_f32_e32 v0, 0x4b800000, v0
	v_trunc_f32_e32 v0, v0
	v_mul_f32_e32 v1, 0x2f800000, v0
	v_floor_f32_e32 v1, v1
	v_fmac_f32_e32 v0, 0xcf800000, v1
	v_cvt_u32_f32_e32 v0, v0
	v_cvt_u32_f32_e32 v1, v1
	global_atomic_add_x2 v[134:135], v[0:1], off offset:1408

.LBB0_1387:
	v_lshl_add_u32 v210, s72, 8, v222
	v_ashrrev_i32_e32 v211, 31, v210
	v_lshl_or_b32 v88, s33, 8, v224
	v_lshlrev_b64 v[90:91], 12, v[210:211]
	v_lshl_add_u64 v[90:91], s[30:31], 0, v[90:91]
	v_ashrrev_i32_e32 v89, 31, v88
	v_lshl_add_u64 v[212:213], v[88:89], 1, v[90:91]
	global_load_dwordx4 v[228:231], v[212:213], off
	global_load_dwordx4 v[186:189], v[212:213], off offset:256
	v_add_co_u32_e32 v88, vcc, 0x10000, v212
	v_readlane_b32 s8, v237, 51
	s_nop 0
	v_addc_co_u32_e32 v89, vcc, 0, v213, vcc
	v_readlane_b32 s11, v237, 54
	global_load_dwordx4 v[182:185], v[88:89], off
	global_load_dwordx4 v[178:181], v[88:89], off offset:256
	v_add_co_u32_e32 v88, vcc, s11, v212
	s_mov_b32 s8, 0x80000
	s_nop 0
	v_addc_co_u32_e32 v89, vcc, 0, v213, vcc
	global_load_dwordx4 v[174:177], v[88:89], off
	global_load_dwordx4 v[170:173], v[88:89], off offset:256
	v_add_co_u32_e32 v88, vcc, 0x30000, v212
	v_and_b32_e32 v227, 64, v214
	s_nop 0
	v_addc_co_u32_e32 v89, vcc, 0, v213, vcc
	global_load_dwordx4 v[166:169], v[88:89], off
	global_load_dwordx4 v[162:165], v[88:89], off offset:256
	v_add_co_u32_e32 v88, vcc, s8, v212
	s_mov_b32 s8, 0xb0000
	s_nop 0
	v_addc_co_u32_e32 v89, vcc, 0, v213, vcc
	global_load_dwordx4 v[154:157], v[88:89], off
	global_load_dwordx4 v[146:149], v[88:89], off offset:256
	v_add_co_u32_e32 v88, vcc, 0x90000, v212
	v_xor_b32_e32 v226, 16, v214
	s_nop 0
	v_addc_co_u32_e32 v89, vcc, 0, v213, vcc
	global_load_dwordx4 v[138:141], v[88:89], off
	global_load_dwordx4 v[130:133], v[88:89], off offset:256
	v_add_co_u32_e32 v88, vcc, 0xa0000, v212
	v_add_u32_e32 v227, 64, v227
	s_nop 0
	v_addc_co_u32_e32 v89, vcc, 0, v213, vcc
	global_load_dwordx4 v[116:119], v[88:89], off
	global_load_dwordx4 v[104:107], v[88:89], off offset:256
	v_add_co_u32_e32 v88, vcc, s8, v212
	v_xor_b32_e32 v232, 32, v214
	s_nop 0
	v_addc_co_u32_e32 v89, vcc, 0, v213, vcc
	global_load_dwordx4 v[92:95], v[88:89], off
	s_nop 0
	global_load_dwordx4 v[88:91], v[88:89], off offset:256
	v_cmp_lt_i32_e32 vcc, v226, v227
	v_readlane_b32 s9, v237, 52
	v_readlane_b32 s10, v237, 53
	v_cndmask_b32_e32 v226, v214, v226, vcc
	v_cmp_lt_i32_e32 vcc, v232, v227
	v_lshlrev_b32_e32 v226, 2, v226
	s_waitcnt vmcnt(0)
	v_and_b32_e32 v233, 0xffff0000, v228
	v_cndmask_b32_e32 v227, v214, v232, vcc
	v_lshlrev_b32_e32 v232, 16, v228
	v_lshlrev_b32_e32 v228, 16, v229
	v_and_b32_e32 v229, 0xffff0000, v229
	v_pk_add_f32 v[160:161], v[160:161], v[228:229]
	v_lshlrev_b32_e32 v228, 16, v230
	v_and_b32_e32 v229, 0xffff0000, v230
	v_pk_add_f32 v[228:229], v[150:151], v[228:229]
	v_lshlrev_b32_e32 v150, 16, v231
	v_and_b32_e32 v151, 0xffff0000, v231
	v_pk_add_f32 v[158:159], v[158:159], v[232:233]
	v_pk_add_f32 v[230:231], v[152:153], v[150:151]
	v_cvt_pk_bf16_f32 v150, v158, v159
	v_cvt_pk_bf16_f32 v151, v160, v161
	v_cvt_pk_bf16_f32 v152, v228, v229
	v_cvt_pk_bf16_f32 v153, v230, v231
	global_store_dwordx4 v[212:213], v[150:153], off sc1
	v_lshlrev_b32_e32 v227, 2, v227
	s_nop 0
	v_pk_mul_f32 v[150:151], v[158:159], v[158:159]
	v_pk_mul_f32 v[158:159], v[228:229], v[228:229]
	v_lshlrev_b32_e32 v228, 16, v186
	v_and_b32_e32 v229, 0xffff0000, v186
	v_lshlrev_b32_e32 v186, 16, v187
	v_and_b32_e32 v187, 0xffff0000, v187
	v_pk_add_f32 v[144:145], v[144:145], v[186:187]
	v_lshlrev_b32_e32 v186, 16, v188
	v_and_b32_e32 v187, 0xffff0000, v188
	v_pk_add_f32 v[186:187], v[134:135], v[186:187]
	v_lshlrev_b32_e32 v134, 16, v189
	v_and_b32_e32 v135, 0xffff0000, v189
	v_pk_add_f32 v[142:143], v[142:143], v[228:229]
	v_pk_add_f32 v[188:189], v[136:137], v[134:135]
	v_cvt_pk_bf16_f32 v134, v142, v143
	v_cvt_pk_bf16_f32 v135, v144, v145
	v_cvt_pk_bf16_f32 v136, v186, v187
	v_cvt_pk_bf16_f32 v137, v188, v189
	global_store_dwordx4 v[212:213], v[134:137], off offset:256 sc1
	v_pk_mul_f32 v[152:153], v[160:161], v[160:161]
	v_pk_mul_f32 v[160:161], v[230:231], v[230:231]
	v_pk_mul_f32 v[134:135], v[142:143], v[142:143]
	v_pk_mul_f32 v[136:137], v[144:145], v[144:145]
	v_add_f32_e32 v134, v134, v135
	v_add_f32_e32 v136, v136, v137
	v_pk_mul_f32 v[142:143], v[186:187], v[186:187]
	v_pk_mul_f32 v[144:145], v[188:189], v[188:189]
	v_add_f32_e32 v134, v134, v136
	v_add_f32_e32 v135, v160, v161
	v_add_f32_e32 v136, v158, v159
	v_add_f32_e32 v144, v144, v145
	v_add_f32_e32 v142, v142, v143
	v_add_f32_e32 v135, v136, v135
	v_add_f32_e32 v136, v152, v153
	v_add_f32_e32 v137, v150, v151
	v_add_f32_e32 v142, v142, v144
	v_add_f32_e32 v136, v137, v136
	v_add_f32_e32 v134, v134, v142
	v_add_f32_e32 v135, v136, v135
	v_add_f32_e32 v134, v135, v134
	v_mov_b32_e32 v242, v134
	v_mov_b32_e32 v243, v134
	s_nop 1
	v_permlane16_swap_b32_e32 v242, v243
	v_add_f32_e32 v134, v242, v243
	v_mov_b32_e32 v242, v134
	v_mov_b32_e32 v243, v134
	s_nop 1
	v_permlane32_swap_b32_e32 v242, v243
	s_and_saveexec_b64 s[8:9], s[40:41]
	s_cbranch_execz .LBB0_1389
	s_waitcnt lgkmcnt(0)
	v_add_f32_e32 v134, v242, v243
	v_mul_f32_e32 v134, 0x4b800000, v134
	v_trunc_f32_e32 v134, v134
	v_mul_f32_e32 v135, 0x2f800000, v134
	v_floor_f32_e32 v135, v135
	v_fmac_f32_e32 v134, 0xcf800000, v135
	v_cvt_u32_f32_e32 v134, v134
	v_cvt_u32_f32_e32 v135, v135
	v_lshl_add_u64 v[136:137], v[210:211], 3, s[46:47]
	global_atomic_add_x2 v[136:137], v[134:135], off
.LBB0_1389:
	s_or_b64 exec, exec, s[8:9]
	v_lshlrev_b32_e32 v142, 16, v182
	v_and_b32_e32 v143, 0xffff0000, v182
	v_pk_add_f32 v[124:125], v[124:125], v[142:143]
	v_lshlrev_b32_e32 v142, 16, v183
	v_and_b32_e32 v143, 0xffff0000, v183
	v_pk_add_f32 v[126:127], v[126:127], v[142:143]
	v_lshlrev_b32_e32 v142, 16, v184
	v_and_b32_e32 v143, 0xffff0000, v184
	v_pk_add_f32 v[142:143], v[120:121], v[142:143]
	v_lshlrev_b32_e32 v120, 16, v185
	v_and_b32_e32 v121, 0xffff0000, v185
	s_mov_b64 s[8:9], 0x10000
	v_pk_add_f32 v[144:145], v[122:123], v[120:121]
	s_waitcnt lgkmcnt(0)
	v_lshl_add_u64 v[134:135], v[212:213], 0, s[8:9]
	v_cvt_pk_bf16_f32 v120, v124, v125
	v_cvt_pk_bf16_f32 v121, v126, v127
	v_cvt_pk_bf16_f32 v122, v142, v143
	v_cvt_pk_bf16_f32 v123, v144, v145
	global_store_dwordx4 v[134:135], v[120:123], off sc1
	v_lshlrev_b32_e32 v134, 16, v178
	v_and_b32_e32 v135, 0xffff0000, v178
	v_pk_add_f32 v[112:113], v[112:113], v[134:135]
	v_lshlrev_b32_e32 v134, 16, v179
	v_and_b32_e32 v135, 0xffff0000, v179
	v_pk_add_f32 v[114:115], v[114:115], v[134:135]
	v_lshlrev_b32_e32 v134, 16, v180
	v_and_b32_e32 v135, 0xffff0000, v180
	v_pk_add_f32 v[134:135], v[108:109], v[134:135]
	v_lshlrev_b32_e32 v108, 16, v181
	v_and_b32_e32 v109, 0xffff0000, v181
	s_mov_b64 s[8:9], 0x10100
	v_pk_mul_f32 v[120:121], v[124:125], v[124:125]
	v_pk_mul_f32 v[124:125], v[142:143], v[142:143]
	v_pk_add_f32 v[142:143], v[110:111], v[108:109]
	v_lshl_add_u64 v[136:137], v[212:213], 0, s[8:9]
	v_cvt_pk_bf16_f32 v108, v112, v113
	v_cvt_pk_bf16_f32 v109, v114, v115
	v_cvt_pk_bf16_f32 v110, v134, v135
	v_cvt_pk_bf16_f32 v111, v142, v143
	global_store_dwordx4 v[136:137], v[108:111], off sc1
	v_pk_mul_f32 v[122:123], v[126:127], v[126:127]
	v_pk_mul_f32 v[126:127], v[144:145], v[144:145]
	v_pk_mul_f32 v[108:109], v[112:113], v[112:113]
	v_pk_mul_f32 v[110:111], v[114:115], v[114:115]
	v_add_f32_e32 v108, v108, v109
	v_add_f32_e32 v110, v110, v111
	v_pk_mul_f32 v[112:113], v[134:135], v[134:135]
	v_pk_mul_f32 v[114:115], v[142:143], v[142:143]
	v_add_f32_e32 v108, v108, v110
	v_add_f32_e32 v109, v126, v127
	v_add_f32_e32 v110, v124, v125
	v_add_f32_e32 v114, v114, v115
	v_add_f32_e32 v112, v112, v113
	v_add_f32_e32 v109, v110, v109
	v_add_f32_e32 v110, v122, v123
	v_add_f32_e32 v111, v120, v121
	v_add_f32_e32 v112, v112, v114
	v_add_f32_e32 v110, v111, v110
	v_add_f32_e32 v108, v108, v112
	v_add_f32_e32 v109, v110, v109
	v_add_f32_e32 v108, v109, v108
	v_mov_b32_e32 v242, v108
	v_mov_b32_e32 v243, v108
	s_nop 1
	v_permlane16_swap_b32_e32 v242, v243
	v_add_f32_e32 v108, v242, v243
	v_mov_b32_e32 v242, v108
	v_mov_b32_e32 v243, v108
	s_nop 1
	v_permlane32_swap_b32_e32 v242, v243
	s_and_saveexec_b64 s[8:9], s[40:41]
	s_cbranch_execz .LBB0_1391
	s_waitcnt lgkmcnt(0)
	v_add_f32_e32 v108, v242, v243
	v_mul_f32_e32 v108, 0x4b800000, v108
	v_trunc_f32_e32 v108, v108
	v_mul_f32_e32 v109, 0x2f800000, v108
	v_floor_f32_e32 v109, v109
	v_fmac_f32_e32 v108, 0xcf800000, v109
	v_cvt_u32_f32_e32 v108, v108
	v_cvt_u32_f32_e32 v109, v109
	v_lshl_add_u64 v[110:111], v[210:211], 3, s[46:47]
	global_atomic_add_x2 v[110:111], v[108:109], off offset:128
.LBB0_1391:
	s_or_b64 exec, exec, s[8:9]
	v_lshlrev_b32_e32 v112, 16, v174
	v_and_b32_e32 v113, 0xffff0000, v174
	v_pk_add_f32 v[100:101], v[100:101], v[112:113]
	v_lshlrev_b32_e32 v112, 16, v175
	v_and_b32_e32 v113, 0xffff0000, v175
	v_pk_add_f32 v[102:103], v[102:103], v[112:113]
	v_lshlrev_b32_e32 v112, 16, v176
	v_and_b32_e32 v113, 0xffff0000, v176
	v_pk_add_f32 v[112:113], v[96:97], v[112:113]
	v_lshlrev_b32_e32 v96, 16, v177
	v_and_b32_e32 v97, 0xffff0000, v177
	s_mov_b64 s[8:9], 0x20000
	v_pk_add_f32 v[114:115], v[98:99], v[96:97]
	s_waitcnt lgkmcnt(0)
	v_lshl_add_u64 v[108:109], v[212:213], 0, s[8:9]
	v_cvt_pk_bf16_f32 v96, v100, v101
	v_cvt_pk_bf16_f32 v97, v102, v103
	v_cvt_pk_bf16_f32 v98, v112, v113
	v_cvt_pk_bf16_f32 v99, v114, v115
	global_store_dwordx4 v[108:109], v[96:99], off sc1
	v_lshlrev_b32_e32 v108, 16, v170
	v_and_b32_e32 v109, 0xffff0000, v170
	v_pk_add_f32 v[84:85], v[84:85], v[108:109]
	v_lshlrev_b32_e32 v108, 16, v171
	v_and_b32_e32 v109, 0xffff0000, v171
	v_pk_add_f32 v[86:87], v[86:87], v[108:109]
	v_lshlrev_b32_e32 v108, 16, v172
	v_and_b32_e32 v109, 0xffff0000, v172
	v_pk_add_f32 v[108:109], v[80:81], v[108:109]
	v_lshlrev_b32_e32 v80, 16, v173
	v_and_b32_e32 v81, 0xffff0000, v173
	s_mov_b64 s[8:9], 0x20100
	v_pk_mul_f32 v[96:97], v[100:101], v[100:101]
	v_pk_mul_f32 v[100:101], v[112:113], v[112:113]
	v_pk_add_f32 v[112:113], v[82:83], v[80:81]
	v_lshl_add_u64 v[110:111], v[212:213], 0, s[8:9]
	v_cvt_pk_bf16_f32 v80, v84, v85
	v_cvt_pk_bf16_f32 v81, v86, v87
	v_cvt_pk_bf16_f32 v82, v108, v109
	v_cvt_pk_bf16_f32 v83, v112, v113
	global_store_dwordx4 v[110:111], v[80:83], off sc1
	v_pk_mul_f32 v[98:99], v[102:103], v[102:103]
	v_pk_mul_f32 v[102:103], v[114:115], v[114:115]
	v_pk_mul_f32 v[80:81], v[84:85], v[84:85]
	v_pk_mul_f32 v[82:83], v[86:87], v[86:87]
	v_add_f32_e32 v80, v80, v81
	v_add_f32_e32 v82, v82, v83
	v_pk_mul_f32 v[84:85], v[108:109], v[108:109]
	v_pk_mul_f32 v[86:87], v[112:113], v[112:113]
	v_add_f32_e32 v80, v80, v82
	v_add_f32_e32 v81, v102, v103
	v_add_f32_e32 v82, v100, v101
	v_add_f32_e32 v86, v86, v87
	v_add_f32_e32 v84, v84, v85
	v_add_f32_e32 v81, v82, v81
	v_add_f32_e32 v82, v98, v99
	v_add_f32_e32 v83, v96, v97
	v_add_f32_e32 v84, v84, v86
	v_add_f32_e32 v82, v83, v82
	v_add_f32_e32 v80, v80, v84
	v_add_f32_e32 v81, v82, v81
	v_add_f32_e32 v80, v81, v80
	v_mov_b32_e32 v242, v80
	v_mov_b32_e32 v243, v80
	s_nop 1
	v_permlane16_swap_b32_e32 v242, v243
	v_add_f32_e32 v80, v242, v243
	v_mov_b32_e32 v242, v80
	v_mov_b32_e32 v243, v80
	s_nop 1
	v_permlane32_swap_b32_e32 v242, v243
	s_and_saveexec_b64 s[8:9], s[40:41]
	s_mov_b64 s[28:29], s[34:35]
	s_cbranch_execz .LBB0_1393
	s_waitcnt lgkmcnt(0)
	v_add_f32_e32 v80, v242, v243
	v_mul_f32_e32 v80, 0x4b800000, v80
	v_trunc_f32_e32 v80, v80
	v_mul_f32_e32 v81, 0x2f800000, v80
	v_floor_f32_e32 v81, v81
	v_fmac_f32_e32 v80, 0xcf800000, v81
	v_cvt_u32_f32_e32 v80, v80
	v_cvt_u32_f32_e32 v81, v81
	v_lshl_add_u64 v[82:83], v[210:211], 3, s[46:47]
	global_atomic_add_x2 v[82:83], v[80:81], off offset:256
.LBB0_1393:
	s_or_b64 exec, exec, s[8:9]
	v_lshlrev_b32_e32 v84, 16, v166
	v_and_b32_e32 v85, 0xffff0000, v166
	v_pk_add_f32 v[76:77], v[76:77], v[84:85]
	v_lshlrev_b32_e32 v84, 16, v167
	v_and_b32_e32 v85, 0xffff0000, v167
	v_pk_add_f32 v[78:79], v[78:79], v[84:85]
	v_lshlrev_b32_e32 v84, 16, v168
	v_and_b32_e32 v85, 0xffff0000, v168
	v_pk_add_f32 v[84:85], v[72:73], v[84:85]
	v_lshlrev_b32_e32 v72, 16, v169
	v_and_b32_e32 v73, 0xffff0000, v169
	s_mov_b64 s[8:9], 0x30000
	v_pk_add_f32 v[86:87], v[74:75], v[72:73]
	s_waitcnt lgkmcnt(0)
	v_lshl_add_u64 v[80:81], v[212:213], 0, s[8:9]
	v_cvt_pk_bf16_f32 v72, v76, v77
	v_cvt_pk_bf16_f32 v73, v78, v79
	v_cvt_pk_bf16_f32 v74, v84, v85
	v_cvt_pk_bf16_f32 v75, v86, v87
	global_store_dwordx4 v[80:81], v[72:75], off sc1
	v_lshlrev_b32_e32 v80, 16, v162
	v_and_b32_e32 v81, 0xffff0000, v162
	v_pk_add_f32 v[68:69], v[68:69], v[80:81]
	v_lshlrev_b32_e32 v80, 16, v163
	v_and_b32_e32 v81, 0xffff0000, v163
	v_pk_add_f32 v[70:71], v[70:71], v[80:81]
	v_lshlrev_b32_e32 v80, 16, v164
	v_and_b32_e32 v81, 0xffff0000, v164
	v_pk_add_f32 v[80:81], v[64:65], v[80:81]
	v_lshlrev_b32_e32 v64, 16, v165
	v_and_b32_e32 v65, 0xffff0000, v165
	s_mov_b64 s[8:9], 0x30100
	v_pk_mul_f32 v[72:73], v[76:77], v[76:77]
	v_pk_mul_f32 v[76:77], v[84:85], v[84:85]
	v_pk_add_f32 v[84:85], v[66:67], v[64:65]
	v_lshl_add_u64 v[82:83], v[212:213], 0, s[8:9]
	v_cvt_pk_bf16_f32 v64, v68, v69
	v_cvt_pk_bf16_f32 v65, v70, v71
	v_cvt_pk_bf16_f32 v66, v80, v81
	v_cvt_pk_bf16_f32 v67, v84, v85
	global_store_dwordx4 v[82:83], v[64:67], off sc1
	v_pk_mul_f32 v[74:75], v[78:79], v[78:79]
	v_pk_mul_f32 v[78:79], v[86:87], v[86:87]
	v_pk_mul_f32 v[64:65], v[68:69], v[68:69]
	v_pk_mul_f32 v[66:67], v[70:71], v[70:71]
	v_add_f32_e32 v64, v64, v65
	v_add_f32_e32 v66, v66, v67
	v_pk_mul_f32 v[68:69], v[80:81], v[80:81]
	v_pk_mul_f32 v[70:71], v[84:85], v[84:85]
	v_add_f32_e32 v64, v64, v66
	v_add_f32_e32 v65, v78, v79
	v_add_f32_e32 v66, v76, v77
	v_add_f32_e32 v70, v70, v71
	v_add_f32_e32 v68, v68, v69
	v_add_f32_e32 v65, v66, v65
	v_add_f32_e32 v66, v74, v75
	v_add_f32_e32 v67, v72, v73
	v_add_f32_e32 v68, v68, v70
	v_add_f32_e32 v66, v67, v66
	v_add_f32_e32 v64, v64, v68
	v_add_f32_e32 v65, v66, v65
	v_add_f32_e32 v64, v65, v64
	v_mov_b32_e32 v242, v64
	v_mov_b32_e32 v243, v64
	s_nop 1
	v_permlane16_swap_b32_e32 v242, v243
	v_add_f32_e32 v64, v242, v243
	v_mov_b32_e32 v242, v64
	v_mov_b32_e32 v243, v64
	s_nop 1
	v_permlane32_swap_b32_e32 v242, v243
	s_and_saveexec_b64 s[8:9], s[40:41]
	s_cbranch_execz .LBB0_1395
	s_waitcnt lgkmcnt(0)
	v_add_f32_e32 v64, v242, v243
	v_mul_f32_e32 v64, 0x4b800000, v64
	v_trunc_f32_e32 v64, v64
	v_mul_f32_e32 v65, 0x2f800000, v64
	v_floor_f32_e32 v65, v65
	v_fmac_f32_e32 v64, 0xcf800000, v65
	v_cvt_u32_f32_e32 v64, v64
	v_cvt_u32_f32_e32 v65, v65
	v_lshl_add_u64 v[66:67], v[210:211], 3, s[46:47]
	global_atomic_add_x2 v[66:67], v[64:65], off offset:384
.LBB0_1395:
	s_or_b64 exec, exec, s[8:9]
	v_lshlrev_b32_e32 v68, 16, v154
	v_and_b32_e32 v69, 0xffff0000, v154
	v_pk_add_f32 v[60:61], v[60:61], v[68:69]
	v_lshlrev_b32_e32 v68, 16, v155
	v_and_b32_e32 v69, 0xffff0000, v155
	v_pk_add_f32 v[62:63], v[62:63], v[68:69]
	v_lshlrev_b32_e32 v68, 16, v156
	v_and_b32_e32 v69, 0xffff0000, v156
	v_pk_add_f32 v[68:69], v[56:57], v[68:69]
	v_lshlrev_b32_e32 v56, 16, v157
	v_and_b32_e32 v57, 0xffff0000, v157
	s_mov_b64 s[8:9], 0x80000
	v_pk_add_f32 v[70:71], v[58:59], v[56:57]
	s_waitcnt lgkmcnt(0)
	v_lshl_add_u64 v[64:65], v[212:213], 0, s[8:9]
	v_cvt_pk_bf16_f32 v56, v60, v61
	v_cvt_pk_bf16_f32 v57, v62, v63
	v_cvt_pk_bf16_f32 v58, v68, v69
	v_cvt_pk_bf16_f32 v59, v70, v71
	global_store_dwordx4 v[64:65], v[56:59], off sc1
	v_lshlrev_b32_e32 v64, 16, v146
	v_and_b32_e32 v65, 0xffff0000, v146
	v_pk_add_f32 v[52:53], v[52:53], v[64:65]
	v_lshlrev_b32_e32 v64, 16, v147
	v_and_b32_e32 v65, 0xffff0000, v147
	v_pk_add_f32 v[54:55], v[54:55], v[64:65]
	v_lshlrev_b32_e32 v64, 16, v148
	v_and_b32_e32 v65, 0xffff0000, v148
	v_pk_add_f32 v[64:65], v[48:49], v[64:65]
	v_lshlrev_b32_e32 v48, 16, v149
	v_and_b32_e32 v49, 0xffff0000, v149
	s_mov_b64 s[8:9], 0x80100
	v_pk_mul_f32 v[56:57], v[60:61], v[60:61]
	v_pk_mul_f32 v[60:61], v[68:69], v[68:69]
	v_pk_add_f32 v[68:69], v[50:51], v[48:49]
	v_lshl_add_u64 v[66:67], v[212:213], 0, s[8:9]
	v_cvt_pk_bf16_f32 v48, v52, v53
	v_cvt_pk_bf16_f32 v49, v54, v55
	v_cvt_pk_bf16_f32 v50, v64, v65
	v_cvt_pk_bf16_f32 v51, v68, v69
	global_store_dwordx4 v[66:67], v[48:51], off sc1
	v_pk_mul_f32 v[58:59], v[62:63], v[62:63]
	v_pk_mul_f32 v[62:63], v[70:71], v[70:71]
	v_pk_mul_f32 v[48:49], v[52:53], v[52:53]
	v_pk_mul_f32 v[50:51], v[54:55], v[54:55]
	v_add_f32_e32 v48, v48, v49
	v_add_f32_e32 v50, v50, v51
	v_pk_mul_f32 v[52:53], v[64:65], v[64:65]
	v_pk_mul_f32 v[54:55], v[68:69], v[68:69]
	v_add_f32_e32 v48, v48, v50
	v_add_f32_e32 v49, v62, v63
	v_add_f32_e32 v50, v60, v61
	v_add_f32_e32 v54, v54, v55
	v_add_f32_e32 v52, v52, v53
	v_add_f32_e32 v49, v50, v49
	v_add_f32_e32 v50, v58, v59
	v_add_f32_e32 v51, v56, v57
	v_add_f32_e32 v52, v52, v54
	v_add_f32_e32 v50, v51, v50
	v_add_f32_e32 v48, v48, v52
	v_add_f32_e32 v49, v50, v49
	v_add_f32_e32 v48, v49, v48
	v_mov_b32_e32 v242, v48
	v_mov_b32_e32 v243, v48
	s_nop 1
	v_permlane16_swap_b32_e32 v242, v243
	v_add_f32_e32 v48, v242, v243
	v_mov_b32_e32 v242, v48
	v_mov_b32_e32 v243, v48
	s_nop 1
	v_permlane32_swap_b32_e32 v242, v243
	s_and_saveexec_b64 s[8:9], s[40:41]
	s_cbranch_execz .LBB0_1397
	s_waitcnt lgkmcnt(0)
	v_add_f32_e32 v48, v242, v243
	v_mul_f32_e32 v48, 0x4b800000, v48
	v_trunc_f32_e32 v48, v48
	v_mul_f32_e32 v49, 0x2f800000, v48
	v_floor_f32_e32 v49, v49
	v_fmac_f32_e32 v48, 0xcf800000, v49
	v_cvt_u32_f32_e32 v48, v48
	v_cvt_u32_f32_e32 v49, v49
	v_lshl_add_u64 v[50:51], v[210:211], 3, s[46:47]
	global_atomic_add_x2 v[50:51], v[48:49], off offset:1024
.LBB0_1397:
	s_or_b64 exec, exec, s[8:9]
	v_lshlrev_b32_e32 v52, 16, v138
	v_and_b32_e32 v53, 0xffff0000, v138
	v_pk_add_f32 v[44:45], v[44:45], v[52:53]
	v_lshlrev_b32_e32 v52, 16, v139
	v_and_b32_e32 v53, 0xffff0000, v139
	v_pk_add_f32 v[46:47], v[46:47], v[52:53]
	v_lshlrev_b32_e32 v52, 16, v140
	v_and_b32_e32 v53, 0xffff0000, v140
	v_pk_add_f32 v[52:53], v[40:41], v[52:53]
	v_lshlrev_b32_e32 v40, 16, v141
	v_and_b32_e32 v41, 0xffff0000, v141
	s_mov_b64 s[8:9], 0x90000
	v_pk_add_f32 v[54:55], v[42:43], v[40:41]
	s_waitcnt lgkmcnt(0)
	v_lshl_add_u64 v[48:49], v[212:213], 0, s[8:9]
	v_cvt_pk_bf16_f32 v40, v44, v45
	v_cvt_pk_bf16_f32 v41, v46, v47
	v_cvt_pk_bf16_f32 v42, v52, v53
	v_cvt_pk_bf16_f32 v43, v54, v55
	global_store_dwordx4 v[48:49], v[40:43], off sc1
	v_lshlrev_b32_e32 v48, 16, v130
	v_and_b32_e32 v49, 0xffff0000, v130
	v_pk_add_f32 v[36:37], v[36:37], v[48:49]
	v_lshlrev_b32_e32 v48, 16, v131
	v_and_b32_e32 v49, 0xffff0000, v131
	v_pk_add_f32 v[38:39], v[38:39], v[48:49]
	v_lshlrev_b32_e32 v48, 16, v132
	v_and_b32_e32 v49, 0xffff0000, v132
	v_pk_add_f32 v[48:49], v[32:33], v[48:49]
	v_lshlrev_b32_e32 v32, 16, v133
	v_and_b32_e32 v33, 0xffff0000, v133
	s_mov_b64 s[8:9], 0x90100
	v_pk_mul_f32 v[40:41], v[44:45], v[44:45]
	v_pk_mul_f32 v[44:45], v[52:53], v[52:53]
	v_pk_add_f32 v[52:53], v[34:35], v[32:33]
	v_lshl_add_u64 v[50:51], v[212:213], 0, s[8:9]
	v_cvt_pk_bf16_f32 v32, v36, v37
	v_cvt_pk_bf16_f32 v33, v38, v39
	v_cvt_pk_bf16_f32 v34, v48, v49
	v_cvt_pk_bf16_f32 v35, v52, v53
	global_store_dwordx4 v[50:51], v[32:35], off sc1
	v_pk_mul_f32 v[42:43], v[46:47], v[46:47]
	v_pk_mul_f32 v[46:47], v[54:55], v[54:55]
	v_pk_mul_f32 v[32:33], v[36:37], v[36:37]
	v_pk_mul_f32 v[34:35], v[38:39], v[38:39]
	v_add_f32_e32 v32, v32, v33
	v_add_f32_e32 v34, v34, v35
	v_pk_mul_f32 v[36:37], v[48:49], v[48:49]
	v_pk_mul_f32 v[38:39], v[52:53], v[52:53]
	v_add_f32_e32 v32, v32, v34
	v_add_f32_e32 v33, v46, v47
	v_add_f32_e32 v34, v44, v45
	v_add_f32_e32 v38, v38, v39
	v_add_f32_e32 v36, v36, v37
	v_add_f32_e32 v33, v34, v33
	v_add_f32_e32 v34, v42, v43
	v_add_f32_e32 v35, v40, v41
	v_add_f32_e32 v36, v36, v38
	v_add_f32_e32 v34, v35, v34
	v_add_f32_e32 v32, v32, v36
	v_add_f32_e32 v33, v34, v33
	v_add_f32_e32 v32, v33, v32
	v_mov_b32_e32 v242, v32
	v_mov_b32_e32 v243, v32
	s_nop 1
	v_permlane16_swap_b32_e32 v242, v243
	v_add_f32_e32 v32, v242, v243
	v_mov_b32_e32 v242, v32
	v_mov_b32_e32 v243, v32
	s_nop 1
	v_permlane32_swap_b32_e32 v242, v243
	s_and_saveexec_b64 s[8:9], s[40:41]
	s_cbranch_execz .LBB0_1399
	s_waitcnt lgkmcnt(0)
	v_add_f32_e32 v32, v242, v243
	v_mul_f32_e32 v32, 0x4b800000, v32
	v_trunc_f32_e32 v32, v32
	v_mul_f32_e32 v33, 0x2f800000, v32
	v_floor_f32_e32 v33, v33
	v_fmac_f32_e32 v32, 0xcf800000, v33
	v_cvt_u32_f32_e32 v32, v32
	v_cvt_u32_f32_e32 v33, v33
	v_lshl_add_u64 v[34:35], v[210:211], 3, s[46:47]
	global_atomic_add_x2 v[34:35], v[32:33], off offset:1152
.LBB0_1399:
	s_or_b64 exec, exec, s[8:9]
	v_lshlrev_b32_e32 v36, 16, v116
	v_and_b32_e32 v37, 0xffff0000, v116
	v_pk_add_f32 v[28:29], v[28:29], v[36:37]
	v_lshlrev_b32_e32 v36, 16, v117
	v_and_b32_e32 v37, 0xffff0000, v117
	v_pk_add_f32 v[30:31], v[30:31], v[36:37]
	v_lshlrev_b32_e32 v36, 16, v118
	v_and_b32_e32 v37, 0xffff0000, v118
	v_pk_add_f32 v[36:37], v[24:25], v[36:37]
	v_lshlrev_b32_e32 v24, 16, v119
	v_and_b32_e32 v25, 0xffff0000, v119
	s_mov_b64 s[8:9], 0xa0000
	v_pk_add_f32 v[38:39], v[26:27], v[24:25]
	s_waitcnt lgkmcnt(0)
	v_lshl_add_u64 v[32:33], v[212:213], 0, s[8:9]
	v_cvt_pk_bf16_f32 v24, v28, v29
	v_cvt_pk_bf16_f32 v25, v30, v31
	v_cvt_pk_bf16_f32 v26, v36, v37
	v_cvt_pk_bf16_f32 v27, v38, v39
	global_store_dwordx4 v[32:33], v[24:27], off sc1
	v_lshlrev_b32_e32 v32, 16, v104
	v_and_b32_e32 v33, 0xffff0000, v104
	v_pk_add_f32 v[20:21], v[20:21], v[32:33]
	v_lshlrev_b32_e32 v32, 16, v105
	v_and_b32_e32 v33, 0xffff0000, v105
	v_pk_add_f32 v[22:23], v[22:23], v[32:33]
	v_lshlrev_b32_e32 v32, 16, v106
	v_and_b32_e32 v33, 0xffff0000, v106
	v_pk_add_f32 v[32:33], v[16:17], v[32:33]
	v_lshlrev_b32_e32 v16, 16, v107
	v_and_b32_e32 v17, 0xffff0000, v107
	s_mov_b64 s[8:9], 0xa0100
	v_pk_mul_f32 v[24:25], v[28:29], v[28:29]
	v_pk_mul_f32 v[28:29], v[36:37], v[36:37]
	v_pk_add_f32 v[36:37], v[18:19], v[16:17]
	v_lshl_add_u64 v[34:35], v[212:213], 0, s[8:9]
	v_cvt_pk_bf16_f32 v16, v20, v21
	v_cvt_pk_bf16_f32 v17, v22, v23
	v_cvt_pk_bf16_f32 v18, v32, v33
	v_cvt_pk_bf16_f32 v19, v36, v37
	global_store_dwordx4 v[34:35], v[16:19], off sc1
	v_pk_mul_f32 v[26:27], v[30:31], v[30:31]
	v_pk_mul_f32 v[30:31], v[38:39], v[38:39]
	v_pk_mul_f32 v[16:17], v[20:21], v[20:21]
	v_pk_mul_f32 v[18:19], v[22:23], v[22:23]
	v_add_f32_e32 v16, v16, v17
	v_add_f32_e32 v18, v18, v19
	v_pk_mul_f32 v[20:21], v[32:33], v[32:33]
	v_pk_mul_f32 v[22:23], v[36:37], v[36:37]
	v_add_f32_e32 v16, v16, v18
	v_add_f32_e32 v17, v30, v31
	v_add_f32_e32 v18, v28, v29
	v_add_f32_e32 v22, v22, v23
	v_add_f32_e32 v20, v20, v21
	v_add_f32_e32 v17, v18, v17
	v_add_f32_e32 v18, v26, v27
	v_add_f32_e32 v19, v24, v25
	v_add_f32_e32 v20, v20, v22
	v_add_f32_e32 v18, v19, v18
	v_add_f32_e32 v16, v16, v20
	v_add_f32_e32 v17, v18, v17
	v_add_f32_e32 v16, v17, v16
	v_mov_b32_e32 v242, v16
	v_mov_b32_e32 v243, v16
	s_nop 1
	v_permlane16_swap_b32_e32 v242, v243
	v_add_f32_e32 v16, v242, v243
	v_mov_b32_e32 v242, v16
	v_mov_b32_e32 v243, v16
	s_nop 1
	v_permlane32_swap_b32_e32 v242, v243
	s_and_saveexec_b64 s[8:9], s[40:41]
	s_cbranch_execz .LBB0_1401
	s_waitcnt lgkmcnt(0)
	v_add_f32_e32 v16, v242, v243
	v_mul_f32_e32 v16, 0x4b800000, v16
	v_trunc_f32_e32 v16, v16
	v_mul_f32_e32 v17, 0x2f800000, v16
	v_floor_f32_e32 v17, v17
	v_fmac_f32_e32 v16, 0xcf800000, v17
	v_cvt_u32_f32_e32 v16, v16
	v_cvt_u32_f32_e32 v17, v17
	v_lshl_add_u64 v[18:19], v[210:211], 3, s[46:47]
	global_atomic_add_x2 v[18:19], v[16:17], off offset:1280
.LBB0_1401:
	s_or_b64 exec, exec, s[8:9]
	v_lshlrev_b32_e32 v20, 16, v92
	v_and_b32_e32 v21, 0xffff0000, v92
	v_pk_add_f32 v[12:13], v[12:13], v[20:21]
	v_lshlrev_b32_e32 v20, 16, v93
	v_and_b32_e32 v21, 0xffff0000, v93
	v_pk_add_f32 v[14:15], v[14:15], v[20:21]
	v_lshlrev_b32_e32 v20, 16, v94
	v_and_b32_e32 v21, 0xffff0000, v94
	v_pk_add_f32 v[20:21], v[8:9], v[20:21]
	v_lshlrev_b32_e32 v8, 16, v95
	v_and_b32_e32 v9, 0xffff0000, v95
	s_mov_b64 s[8:9], 0xb0000
	v_pk_add_f32 v[22:23], v[10:11], v[8:9]
	s_waitcnt lgkmcnt(0)
	v_lshl_add_u64 v[16:17], v[212:213], 0, s[8:9]
	v_cvt_pk_bf16_f32 v8, v12, v13
	v_cvt_pk_bf16_f32 v9, v14, v15
	v_cvt_pk_bf16_f32 v10, v20, v21
	v_cvt_pk_bf16_f32 v11, v22, v23
	global_store_dwordx4 v[16:17], v[8:11], off sc1
	v_lshlrev_b32_e32 v16, 16, v88
	v_and_b32_e32 v17, 0xffff0000, v88
	v_pk_add_f32 v[4:5], v[4:5], v[16:17]
	v_lshlrev_b32_e32 v16, 16, v89
	v_and_b32_e32 v17, 0xffff0000, v89
	v_pk_add_f32 v[6:7], v[6:7], v[16:17]
	v_lshlrev_b32_e32 v16, 16, v90
	v_and_b32_e32 v17, 0xffff0000, v90
	v_pk_add_f32 v[16:17], v[0:1], v[16:17]
	v_lshlrev_b32_e32 v0, 16, v91
	v_and_b32_e32 v1, 0xffff0000, v91
	s_mov_b64 s[8:9], 0xb0100
	v_pk_mul_f32 v[8:9], v[12:13], v[12:13]
	v_pk_mul_f32 v[12:13], v[20:21], v[20:21]
	v_pk_add_f32 v[20:21], v[2:3], v[0:1]
	v_lshl_add_u64 v[18:19], v[212:213], 0, s[8:9]
	v_cvt_pk_bf16_f32 v0, v4, v5
	v_cvt_pk_bf16_f32 v1, v6, v7
	v_cvt_pk_bf16_f32 v2, v16, v17
	v_cvt_pk_bf16_f32 v3, v20, v21
	global_store_dwordx4 v[18:19], v[0:3], off sc1
	v_pk_mul_f32 v[10:11], v[14:15], v[14:15]
	v_pk_mul_f32 v[14:15], v[22:23], v[22:23]
	v_pk_mul_f32 v[0:1], v[4:5], v[4:5]
	v_pk_mul_f32 v[2:3], v[6:7], v[6:7]
	v_add_f32_e32 v0, v0, v1
	v_add_f32_e32 v2, v2, v3
	v_pk_mul_f32 v[4:5], v[16:17], v[16:17]
	v_pk_mul_f32 v[6:7], v[20:21], v[20:21]
	v_add_f32_e32 v0, v0, v2
	v_add_f32_e32 v1, v14, v15
	v_add_f32_e32 v2, v12, v13
	v_add_f32_e32 v6, v6, v7
	v_add_f32_e32 v4, v4, v5
	v_add_f32_e32 v1, v2, v1
	v_add_f32_e32 v2, v10, v11
	v_add_f32_e32 v3, v8, v9
	v_add_f32_e32 v4, v4, v6
	v_add_f32_e32 v2, v3, v2
	v_add_f32_e32 v0, v0, v4
	v_add_f32_e32 v1, v2, v1
	v_add_f32_e32 v0, v1, v0
	v_mov_b32_e32 v242, v0
	v_mov_b32_e32 v243, v0
	s_nop 1
	v_permlane16_swap_b32_e32 v242, v243
	v_add_f32_e32 v0, v242, v243
	v_mov_b32_e32 v242, v0
	v_mov_b32_e32 v243, v0
	s_nop 1
	v_permlane32_swap_b32_e32 v242, v243
	s_and_saveexec_b64 s[8:9], s[40:41]
	s_cbranch_execz .LBB0_1403
	s_waitcnt lgkmcnt(0)
	v_add_f32_e32 v0, v242, v243
	v_mul_f32_e32 v0, 0x4b800000, v0
	v_trunc_f32_e32 v0, v0
	v_mul_f32_e32 v1, 0x2f800000, v0
	v_floor_f32_e32 v1, v1
	v_fmac_f32_e32 v0, 0xcf800000, v1
	v_cvt_u32_f32_e32 v0, v0
	v_cvt_u32_f32_e32 v1, v1
	v_lshl_add_u64 v[2:3], v[210:211], 3, s[46:47]
	global_atomic_add_x2 v[2:3], v[0:1], off offset:1408

.LBB0_1621:
	v_lshl_add_u32 v210, s74, 8, v222
	v_ashrrev_i32_e32 v211, 31, v210
	v_lshl_or_b32 v88, s73, 8, v224
	v_lshlrev_b64 v[90:91], 12, v[210:211]
	v_lshl_add_u64 v[90:91], s[30:31], 0, v[90:91]
	v_ashrrev_i32_e32 v89, 31, v88
	v_lshl_add_u64 v[212:213], v[88:89], 1, v[90:91]
	global_load_dwordx4 v[228:231], v[212:213], off
	global_load_dwordx4 v[186:189], v[212:213], off offset:256
	v_add_co_u32_e32 v88, vcc, 0x10000, v212
	v_readlane_b32 s8, v237, 51
	s_nop 0
	v_addc_co_u32_e32 v89, vcc, 0, v213, vcc
	v_readlane_b32 s11, v237, 54
	global_load_dwordx4 v[182:185], v[88:89], off
	global_load_dwordx4 v[178:181], v[88:89], off offset:256
	v_add_co_u32_e32 v88, vcc, s11, v212
	s_mov_b32 s8, 0x80000
	s_nop 0
	v_addc_co_u32_e32 v89, vcc, 0, v213, vcc
	global_load_dwordx4 v[174:177], v[88:89], off
	global_load_dwordx4 v[170:173], v[88:89], off offset:256
	v_add_co_u32_e32 v88, vcc, 0x30000, v212
	v_and_b32_e32 v227, 64, v214
	s_nop 0
	v_addc_co_u32_e32 v89, vcc, 0, v213, vcc
	global_load_dwordx4 v[166:169], v[88:89], off
	global_load_dwordx4 v[162:165], v[88:89], off offset:256
	v_add_co_u32_e32 v88, vcc, s8, v212
	s_mov_b32 s8, 0xb0000
	s_nop 0
	v_addc_co_u32_e32 v89, vcc, 0, v213, vcc
	global_load_dwordx4 v[154:157], v[88:89], off
	global_load_dwordx4 v[146:149], v[88:89], off offset:256
	v_add_co_u32_e32 v88, vcc, 0x90000, v212
	v_xor_b32_e32 v226, 16, v214
	s_nop 0
	v_addc_co_u32_e32 v89, vcc, 0, v213, vcc
	global_load_dwordx4 v[134:137], v[88:89], off
	global_load_dwordx4 v[130:133], v[88:89], off offset:256
	v_add_co_u32_e32 v88, vcc, 0xa0000, v212
	v_add_u32_e32 v227, 64, v227
	s_nop 0
	v_addc_co_u32_e32 v89, vcc, 0, v213, vcc
	global_load_dwordx4 v[116:119], v[88:89], off
	global_load_dwordx4 v[104:107], v[88:89], off offset:256
	v_add_co_u32_e32 v88, vcc, s8, v212
	v_xor_b32_e32 v232, 32, v214
	s_nop 0
	v_addc_co_u32_e32 v89, vcc, 0, v213, vcc
	global_load_dwordx4 v[92:95], v[88:89], off
	s_nop 0
	global_load_dwordx4 v[88:91], v[88:89], off offset:256
	v_cmp_lt_i32_e32 vcc, v226, v227
	v_readlane_b32 s9, v237, 52
	v_readlane_b32 s10, v237, 53
	v_cndmask_b32_e32 v226, v214, v226, vcc
	v_cmp_lt_i32_e32 vcc, v232, v227
	v_lshlrev_b32_e32 v226, 2, v226
	s_waitcnt vmcnt(0)
	v_and_b32_e32 v233, 0xffff0000, v228
	v_cndmask_b32_e32 v227, v214, v232, vcc
	v_lshlrev_b32_e32 v232, 16, v228
	v_lshlrev_b32_e32 v228, 16, v229
	v_and_b32_e32 v229, 0xffff0000, v229
	v_pk_add_f32 v[160:161], v[160:161], v[228:229]
	v_lshlrev_b32_e32 v228, 16, v230
	v_and_b32_e32 v229, 0xffff0000, v230
	v_pk_add_f32 v[228:229], v[150:151], v[228:229]
	v_lshlrev_b32_e32 v150, 16, v231
	v_and_b32_e32 v151, 0xffff0000, v231
	v_pk_add_f32 v[158:159], v[158:159], v[232:233]
	v_pk_add_f32 v[230:231], v[152:153], v[150:151]
	v_cvt_pk_bf16_f32 v150, v158, v159
	v_cvt_pk_bf16_f32 v151, v160, v161
	v_cvt_pk_bf16_f32 v152, v228, v229
	v_cvt_pk_bf16_f32 v153, v230, v231
	global_store_dwordx4 v[212:213], v[150:153], off sc1
	v_lshlrev_b32_e32 v227, 2, v227
	s_nop 0
	v_pk_mul_f32 v[150:151], v[158:159], v[158:159]
	v_pk_mul_f32 v[158:159], v[228:229], v[228:229]
	v_lshlrev_b32_e32 v228, 16, v186
	v_and_b32_e32 v229, 0xffff0000, v186
	v_lshlrev_b32_e32 v186, 16, v187
	v_and_b32_e32 v187, 0xffff0000, v187
	v_pk_add_f32 v[144:145], v[144:145], v[186:187]
	v_lshlrev_b32_e32 v186, 16, v188
	v_and_b32_e32 v187, 0xffff0000, v188
	v_pk_add_f32 v[186:187], v[138:139], v[186:187]
	v_lshlrev_b32_e32 v138, 16, v189
	v_and_b32_e32 v139, 0xffff0000, v189
	v_pk_add_f32 v[142:143], v[142:143], v[228:229]
	v_pk_add_f32 v[188:189], v[140:141], v[138:139]
	v_cvt_pk_bf16_f32 v138, v142, v143
	v_cvt_pk_bf16_f32 v139, v144, v145
	v_cvt_pk_bf16_f32 v140, v186, v187
	v_cvt_pk_bf16_f32 v141, v188, v189
	global_store_dwordx4 v[212:213], v[138:141], off offset:256 sc1
	v_pk_mul_f32 v[152:153], v[160:161], v[160:161]
	v_pk_mul_f32 v[160:161], v[230:231], v[230:231]
	v_pk_mul_f32 v[138:139], v[142:143], v[142:143]
	v_pk_mul_f32 v[140:141], v[144:145], v[144:145]
	v_add_f32_e32 v138, v138, v139
	v_add_f32_e32 v140, v140, v141
	v_pk_mul_f32 v[142:143], v[186:187], v[186:187]
	v_pk_mul_f32 v[144:145], v[188:189], v[188:189]
	v_add_f32_e32 v138, v138, v140
	v_add_f32_e32 v139, v160, v161
	v_add_f32_e32 v140, v158, v159
	v_add_f32_e32 v144, v144, v145
	v_add_f32_e32 v142, v142, v143
	v_add_f32_e32 v139, v140, v139
	v_add_f32_e32 v140, v152, v153
	v_add_f32_e32 v141, v150, v151
	v_add_f32_e32 v142, v142, v144
	v_add_f32_e32 v140, v141, v140
	v_add_f32_e32 v138, v138, v142
	v_add_f32_e32 v139, v140, v139
	v_add_f32_e32 v138, v139, v138
	v_mov_b32_e32 v242, v138
	v_mov_b32_e32 v243, v138
	s_nop 1
	v_permlane16_swap_b32_e32 v242, v243
	v_add_f32_e32 v138, v242, v243
	v_mov_b32_e32 v242, v138
	v_mov_b32_e32 v243, v138
	s_nop 1
	v_permlane32_swap_b32_e32 v242, v243
	s_and_saveexec_b64 s[8:9], s[38:39]
	s_cbranch_execz .LBB0_1623
	s_waitcnt lgkmcnt(0)
	v_add_f32_e32 v138, v242, v243
	v_mul_f32_e32 v138, 0x4b800000, v138
	v_trunc_f32_e32 v138, v138
	v_mul_f32_e32 v139, 0x2f800000, v138
	v_floor_f32_e32 v139, v139
	v_fmac_f32_e32 v138, 0xcf800000, v139
	v_cvt_u32_f32_e32 v138, v138
	v_cvt_u32_f32_e32 v139, v139
	v_lshl_add_u64 v[140:141], v[210:211], 3, s[44:45]
	global_atomic_add_x2 v[140:141], v[138:139], off
.LBB0_1623:
	s_or_b64 exec, exec, s[8:9]
	v_lshlrev_b32_e32 v142, 16, v182
	v_and_b32_e32 v143, 0xffff0000, v182
	v_pk_add_f32 v[124:125], v[124:125], v[142:143]
	v_lshlrev_b32_e32 v142, 16, v183
	v_and_b32_e32 v143, 0xffff0000, v183
	v_pk_add_f32 v[126:127], v[126:127], v[142:143]
	v_lshlrev_b32_e32 v142, 16, v184
	v_and_b32_e32 v143, 0xffff0000, v184
	v_pk_add_f32 v[142:143], v[120:121], v[142:143]
	v_lshlrev_b32_e32 v120, 16, v185
	v_and_b32_e32 v121, 0xffff0000, v185
	s_mov_b64 s[8:9], 0x10000
	v_pk_add_f32 v[144:145], v[122:123], v[120:121]
	s_waitcnt lgkmcnt(0)
	v_lshl_add_u64 v[138:139], v[212:213], 0, s[8:9]
	v_cvt_pk_bf16_f32 v120, v124, v125
	v_cvt_pk_bf16_f32 v121, v126, v127
	v_cvt_pk_bf16_f32 v122, v142, v143
	v_cvt_pk_bf16_f32 v123, v144, v145
	global_store_dwordx4 v[138:139], v[120:123], off sc1
	v_lshlrev_b32_e32 v138, 16, v178
	v_and_b32_e32 v139, 0xffff0000, v178
	v_pk_add_f32 v[112:113], v[112:113], v[138:139]
	v_lshlrev_b32_e32 v138, 16, v179
	v_and_b32_e32 v139, 0xffff0000, v179
	v_pk_add_f32 v[114:115], v[114:115], v[138:139]
	v_lshlrev_b32_e32 v138, 16, v180
	v_and_b32_e32 v139, 0xffff0000, v180
	v_pk_add_f32 v[138:139], v[108:109], v[138:139]
	v_lshlrev_b32_e32 v108, 16, v181
	v_and_b32_e32 v109, 0xffff0000, v181
	s_mov_b64 s[8:9], 0x10100
	v_pk_mul_f32 v[120:121], v[124:125], v[124:125]
	v_pk_mul_f32 v[124:125], v[142:143], v[142:143]
	v_pk_add_f32 v[142:143], v[110:111], v[108:109]
	v_lshl_add_u64 v[140:141], v[212:213], 0, s[8:9]
	v_cvt_pk_bf16_f32 v108, v112, v113
	v_cvt_pk_bf16_f32 v109, v114, v115
	v_cvt_pk_bf16_f32 v110, v138, v139
	v_cvt_pk_bf16_f32 v111, v142, v143
	global_store_dwordx4 v[140:141], v[108:111], off sc1
	v_pk_mul_f32 v[122:123], v[126:127], v[126:127]
	v_pk_mul_f32 v[126:127], v[144:145], v[144:145]
	v_pk_mul_f32 v[108:109], v[112:113], v[112:113]
	v_pk_mul_f32 v[110:111], v[114:115], v[114:115]
	v_add_f32_e32 v108, v108, v109
	v_add_f32_e32 v110, v110, v111
	v_pk_mul_f32 v[112:113], v[138:139], v[138:139]
	v_pk_mul_f32 v[114:115], v[142:143], v[142:143]
	v_add_f32_e32 v108, v108, v110
	v_add_f32_e32 v109, v126, v127
	v_add_f32_e32 v110, v124, v125
	v_add_f32_e32 v114, v114, v115
	v_add_f32_e32 v112, v112, v113
	v_add_f32_e32 v109, v110, v109
	v_add_f32_e32 v110, v122, v123
	v_add_f32_e32 v111, v120, v121
	v_add_f32_e32 v112, v112, v114
	v_add_f32_e32 v110, v111, v110
	v_add_f32_e32 v108, v108, v112
	v_add_f32_e32 v109, v110, v109
	v_add_f32_e32 v108, v109, v108
	v_mov_b32_e32 v242, v108
	v_mov_b32_e32 v243, v108
	s_nop 1
	v_permlane16_swap_b32_e32 v242, v243
	v_add_f32_e32 v108, v242, v243
	v_mov_b32_e32 v242, v108
	v_mov_b32_e32 v243, v108
	s_nop 1
	v_permlane32_swap_b32_e32 v242, v243
	s_and_saveexec_b64 s[8:9], s[38:39]
	s_cbranch_execz .LBB0_1625
	s_waitcnt lgkmcnt(0)
	v_add_f32_e32 v108, v242, v243
	v_mul_f32_e32 v108, 0x4b800000, v108
	v_trunc_f32_e32 v108, v108
	v_mul_f32_e32 v109, 0x2f800000, v108
	v_floor_f32_e32 v109, v109
	v_fmac_f32_e32 v108, 0xcf800000, v109
	v_cvt_u32_f32_e32 v108, v108
	v_cvt_u32_f32_e32 v109, v109
	v_lshl_add_u64 v[110:111], v[210:211], 3, s[44:45]
	global_atomic_add_x2 v[110:111], v[108:109], off offset:128
.LBB0_1625:
	s_or_b64 exec, exec, s[8:9]
	v_lshlrev_b32_e32 v112, 16, v174
	v_and_b32_e32 v113, 0xffff0000, v174
	v_pk_add_f32 v[100:101], v[100:101], v[112:113]
	v_lshlrev_b32_e32 v112, 16, v175
	v_and_b32_e32 v113, 0xffff0000, v175
	v_pk_add_f32 v[102:103], v[102:103], v[112:113]
	v_lshlrev_b32_e32 v112, 16, v176
	v_and_b32_e32 v113, 0xffff0000, v176
	v_pk_add_f32 v[112:113], v[96:97], v[112:113]
	v_lshlrev_b32_e32 v96, 16, v177
	v_and_b32_e32 v97, 0xffff0000, v177
	s_mov_b64 s[8:9], 0x20000
	v_pk_add_f32 v[114:115], v[98:99], v[96:97]
	s_waitcnt lgkmcnt(0)
	v_lshl_add_u64 v[108:109], v[212:213], 0, s[8:9]
	v_cvt_pk_bf16_f32 v96, v100, v101
	v_cvt_pk_bf16_f32 v97, v102, v103
	v_cvt_pk_bf16_f32 v98, v112, v113
	v_cvt_pk_bf16_f32 v99, v114, v115
	global_store_dwordx4 v[108:109], v[96:99], off sc1
	v_lshlrev_b32_e32 v108, 16, v170
	v_and_b32_e32 v109, 0xffff0000, v170
	v_pk_add_f32 v[84:85], v[84:85], v[108:109]
	v_lshlrev_b32_e32 v108, 16, v171
	v_and_b32_e32 v109, 0xffff0000, v171
	v_pk_add_f32 v[86:87], v[86:87], v[108:109]
	v_lshlrev_b32_e32 v108, 16, v172
	v_and_b32_e32 v109, 0xffff0000, v172
	v_pk_add_f32 v[108:109], v[80:81], v[108:109]
	v_lshlrev_b32_e32 v80, 16, v173
	v_and_b32_e32 v81, 0xffff0000, v173
	s_mov_b64 s[8:9], 0x20100
	v_pk_mul_f32 v[96:97], v[100:101], v[100:101]
	v_pk_mul_f32 v[100:101], v[112:113], v[112:113]
	v_pk_add_f32 v[112:113], v[82:83], v[80:81]
	v_lshl_add_u64 v[110:111], v[212:213], 0, s[8:9]
	v_cvt_pk_bf16_f32 v80, v84, v85
	v_cvt_pk_bf16_f32 v81, v86, v87
	v_cvt_pk_bf16_f32 v82, v108, v109
	v_cvt_pk_bf16_f32 v83, v112, v113
	global_store_dwordx4 v[110:111], v[80:83], off sc1
	v_pk_mul_f32 v[98:99], v[102:103], v[102:103]
	v_pk_mul_f32 v[102:103], v[114:115], v[114:115]
	v_pk_mul_f32 v[80:81], v[84:85], v[84:85]
	v_pk_mul_f32 v[82:83], v[86:87], v[86:87]
	v_add_f32_e32 v80, v80, v81
	v_add_f32_e32 v82, v82, v83
	v_pk_mul_f32 v[84:85], v[108:109], v[108:109]
	v_pk_mul_f32 v[86:87], v[112:113], v[112:113]
	v_add_f32_e32 v80, v80, v82
	v_add_f32_e32 v81, v102, v103
	v_add_f32_e32 v82, v100, v101
	v_add_f32_e32 v86, v86, v87
	v_add_f32_e32 v84, v84, v85
	v_add_f32_e32 v81, v82, v81
	v_add_f32_e32 v82, v98, v99
	v_add_f32_e32 v83, v96, v97
	v_add_f32_e32 v84, v84, v86
	v_add_f32_e32 v82, v83, v82
	v_add_f32_e32 v80, v80, v84
	v_add_f32_e32 v81, v82, v81
	v_add_f32_e32 v80, v81, v80
	v_mov_b32_e32 v242, v80
	v_mov_b32_e32 v243, v80
	s_nop 1
	v_permlane16_swap_b32_e32 v242, v243
	v_add_f32_e32 v80, v242, v243
	v_mov_b32_e32 v242, v80
	v_mov_b32_e32 v243, v80
	s_nop 1
	v_permlane32_swap_b32_e32 v242, v243
	s_and_saveexec_b64 s[8:9], s[38:39]
	s_cbranch_execz .LBB0_1627
	s_waitcnt lgkmcnt(0)
	v_add_f32_e32 v80, v242, v243
	v_mul_f32_e32 v80, 0x4b800000, v80
	v_trunc_f32_e32 v80, v80
	v_mul_f32_e32 v81, 0x2f800000, v80
	v_floor_f32_e32 v81, v81
	v_fmac_f32_e32 v80, 0xcf800000, v81
	v_cvt_u32_f32_e32 v80, v80
	v_cvt_u32_f32_e32 v81, v81
	v_lshl_add_u64 v[82:83], v[210:211], 3, s[44:45]
	global_atomic_add_x2 v[82:83], v[80:81], off offset:256
.LBB0_1627:
	s_or_b64 exec, exec, s[8:9]
	v_lshlrev_b32_e32 v84, 16, v166
	v_and_b32_e32 v85, 0xffff0000, v166
	v_pk_add_f32 v[76:77], v[76:77], v[84:85]
	v_lshlrev_b32_e32 v84, 16, v167
	v_and_b32_e32 v85, 0xffff0000, v167
	v_pk_add_f32 v[78:79], v[78:79], v[84:85]
	v_lshlrev_b32_e32 v84, 16, v168
	v_and_b32_e32 v85, 0xffff0000, v168
	v_pk_add_f32 v[84:85], v[72:73], v[84:85]
	v_lshlrev_b32_e32 v72, 16, v169
	v_and_b32_e32 v73, 0xffff0000, v169
	s_mov_b64 s[8:9], 0x30000
	v_pk_add_f32 v[86:87], v[74:75], v[72:73]
	s_waitcnt lgkmcnt(0)
	v_lshl_add_u64 v[80:81], v[212:213], 0, s[8:9]
	v_cvt_pk_bf16_f32 v72, v76, v77
	v_cvt_pk_bf16_f32 v73, v78, v79
	v_cvt_pk_bf16_f32 v74, v84, v85
	v_cvt_pk_bf16_f32 v75, v86, v87
	global_store_dwordx4 v[80:81], v[72:75], off sc1
	v_lshlrev_b32_e32 v80, 16, v162
	v_and_b32_e32 v81, 0xffff0000, v162
	v_pk_add_f32 v[68:69], v[68:69], v[80:81]
	v_lshlrev_b32_e32 v80, 16, v163
	v_and_b32_e32 v81, 0xffff0000, v163
	v_pk_add_f32 v[70:71], v[70:71], v[80:81]
	v_lshlrev_b32_e32 v80, 16, v164
	v_and_b32_e32 v81, 0xffff0000, v164
	v_pk_add_f32 v[80:81], v[64:65], v[80:81]
	v_lshlrev_b32_e32 v64, 16, v165
	v_and_b32_e32 v65, 0xffff0000, v165
	s_mov_b64 s[8:9], 0x30100
	v_pk_mul_f32 v[72:73], v[76:77], v[76:77]
	v_pk_mul_f32 v[76:77], v[84:85], v[84:85]
	v_pk_add_f32 v[84:85], v[66:67], v[64:65]
	v_lshl_add_u64 v[82:83], v[212:213], 0, s[8:9]
	v_cvt_pk_bf16_f32 v64, v68, v69
	v_cvt_pk_bf16_f32 v65, v70, v71
	v_cvt_pk_bf16_f32 v66, v80, v81
	v_cvt_pk_bf16_f32 v67, v84, v85
	global_store_dwordx4 v[82:83], v[64:67], off sc1
	v_pk_mul_f32 v[74:75], v[78:79], v[78:79]
	v_pk_mul_f32 v[78:79], v[86:87], v[86:87]
	v_pk_mul_f32 v[64:65], v[68:69], v[68:69]
	v_pk_mul_f32 v[66:67], v[70:71], v[70:71]
	v_add_f32_e32 v64, v64, v65
	v_add_f32_e32 v66, v66, v67
	v_pk_mul_f32 v[68:69], v[80:81], v[80:81]
	v_pk_mul_f32 v[70:71], v[84:85], v[84:85]
	v_add_f32_e32 v64, v64, v66
	v_add_f32_e32 v65, v78, v79
	v_add_f32_e32 v66, v76, v77
	v_add_f32_e32 v70, v70, v71
	v_add_f32_e32 v68, v68, v69
	v_add_f32_e32 v65, v66, v65
	v_add_f32_e32 v66, v74, v75
	v_add_f32_e32 v67, v72, v73
	v_add_f32_e32 v68, v68, v70
	v_add_f32_e32 v66, v67, v66
	v_add_f32_e32 v64, v64, v68
	v_add_f32_e32 v65, v66, v65
	v_add_f32_e32 v64, v65, v64
	v_mov_b32_e32 v242, v64
	v_mov_b32_e32 v243, v64
	s_nop 1
	v_permlane16_swap_b32_e32 v242, v243
	v_add_f32_e32 v64, v242, v243
	v_mov_b32_e32 v242, v64
	v_mov_b32_e32 v243, v64
	s_nop 1
	v_permlane32_swap_b32_e32 v242, v243
	s_and_saveexec_b64 s[8:9], s[38:39]
	s_cbranch_execz .LBB0_1629
	s_waitcnt lgkmcnt(0)
	v_add_f32_e32 v64, v242, v243
	v_mul_f32_e32 v64, 0x4b800000, v64
	v_trunc_f32_e32 v64, v64
	v_mul_f32_e32 v65, 0x2f800000, v64
	v_floor_f32_e32 v65, v65
	v_fmac_f32_e32 v64, 0xcf800000, v65
	v_cvt_u32_f32_e32 v64, v64
	v_cvt_u32_f32_e32 v65, v65
	v_lshl_add_u64 v[66:67], v[210:211], 3, s[44:45]
	global_atomic_add_x2 v[66:67], v[64:65], off offset:384
.LBB0_1629:
	s_or_b64 exec, exec, s[8:9]
	v_lshlrev_b32_e32 v68, 16, v154
	v_and_b32_e32 v69, 0xffff0000, v154
	v_pk_add_f32 v[60:61], v[60:61], v[68:69]
	v_lshlrev_b32_e32 v68, 16, v155
	v_and_b32_e32 v69, 0xffff0000, v155
	v_pk_add_f32 v[62:63], v[62:63], v[68:69]
	v_lshlrev_b32_e32 v68, 16, v156
	v_and_b32_e32 v69, 0xffff0000, v156
	v_pk_add_f32 v[68:69], v[56:57], v[68:69]
	v_lshlrev_b32_e32 v56, 16, v157
	v_and_b32_e32 v57, 0xffff0000, v157
	s_mov_b64 s[8:9], 0x80000
	v_pk_add_f32 v[70:71], v[58:59], v[56:57]
	s_waitcnt lgkmcnt(0)
	v_lshl_add_u64 v[64:65], v[212:213], 0, s[8:9]
	v_cvt_pk_bf16_f32 v56, v60, v61
	v_cvt_pk_bf16_f32 v57, v62, v63
	v_cvt_pk_bf16_f32 v58, v68, v69
	v_cvt_pk_bf16_f32 v59, v70, v71
	global_store_dwordx4 v[64:65], v[56:59], off sc1
	v_lshlrev_b32_e32 v64, 16, v146
	v_and_b32_e32 v65, 0xffff0000, v146
	v_pk_add_f32 v[52:53], v[52:53], v[64:65]
	v_lshlrev_b32_e32 v64, 16, v147
	v_and_b32_e32 v65, 0xffff0000, v147
	v_pk_add_f32 v[54:55], v[54:55], v[64:65]
	v_lshlrev_b32_e32 v64, 16, v148
	v_and_b32_e32 v65, 0xffff0000, v148
	v_pk_add_f32 v[64:65], v[48:49], v[64:65]
	v_lshlrev_b32_e32 v48, 16, v149
	v_and_b32_e32 v49, 0xffff0000, v149
	s_mov_b64 s[8:9], 0x80100
	v_pk_mul_f32 v[56:57], v[60:61], v[60:61]
	v_pk_mul_f32 v[60:61], v[68:69], v[68:69]
	v_pk_add_f32 v[68:69], v[50:51], v[48:49]
	v_lshl_add_u64 v[66:67], v[212:213], 0, s[8:9]
	v_cvt_pk_bf16_f32 v48, v52, v53
	v_cvt_pk_bf16_f32 v49, v54, v55
	v_cvt_pk_bf16_f32 v50, v64, v65
	v_cvt_pk_bf16_f32 v51, v68, v69
	global_store_dwordx4 v[66:67], v[48:51], off sc1
	v_pk_mul_f32 v[58:59], v[62:63], v[62:63]
	v_pk_mul_f32 v[62:63], v[70:71], v[70:71]
	v_pk_mul_f32 v[48:49], v[52:53], v[52:53]
	v_pk_mul_f32 v[50:51], v[54:55], v[54:55]
	v_add_f32_e32 v48, v48, v49
	v_add_f32_e32 v50, v50, v51
	v_pk_mul_f32 v[52:53], v[64:65], v[64:65]
	v_pk_mul_f32 v[54:55], v[68:69], v[68:69]
	v_add_f32_e32 v48, v48, v50
	v_add_f32_e32 v49, v62, v63
	v_add_f32_e32 v50, v60, v61
	v_add_f32_e32 v54, v54, v55
	v_add_f32_e32 v52, v52, v53
	v_add_f32_e32 v49, v50, v49
	v_add_f32_e32 v50, v58, v59
	v_add_f32_e32 v51, v56, v57
	v_add_f32_e32 v52, v52, v54
	v_add_f32_e32 v50, v51, v50
	v_add_f32_e32 v48, v48, v52
	v_add_f32_e32 v49, v50, v49
	v_add_f32_e32 v48, v49, v48
	v_mov_b32_e32 v242, v48
	v_mov_b32_e32 v243, v48
	s_nop 1
	v_permlane16_swap_b32_e32 v242, v243
	v_add_f32_e32 v48, v242, v243
	v_mov_b32_e32 v242, v48
	v_mov_b32_e32 v243, v48
	s_nop 1
	v_permlane32_swap_b32_e32 v242, v243
	s_and_saveexec_b64 s[8:9], s[38:39]
	s_cbranch_execz .LBB0_1631
	s_waitcnt lgkmcnt(0)
	v_add_f32_e32 v48, v242, v243
	v_mul_f32_e32 v48, 0x4b800000, v48
	v_trunc_f32_e32 v48, v48
	v_mul_f32_e32 v49, 0x2f800000, v48
	v_floor_f32_e32 v49, v49
	v_fmac_f32_e32 v48, 0xcf800000, v49
	v_cvt_u32_f32_e32 v48, v48
	v_cvt_u32_f32_e32 v49, v49
	v_lshl_add_u64 v[50:51], v[210:211], 3, s[44:45]
	global_atomic_add_x2 v[50:51], v[48:49], off offset:1024
.LBB0_1631:
	s_or_b64 exec, exec, s[8:9]
	v_lshlrev_b32_e32 v52, 16, v134
	v_and_b32_e32 v53, 0xffff0000, v134
	v_pk_add_f32 v[44:45], v[44:45], v[52:53]
	v_lshlrev_b32_e32 v52, 16, v135
	v_and_b32_e32 v53, 0xffff0000, v135
	v_pk_add_f32 v[46:47], v[46:47], v[52:53]
	v_lshlrev_b32_e32 v52, 16, v136
	v_and_b32_e32 v53, 0xffff0000, v136
	v_pk_add_f32 v[52:53], v[40:41], v[52:53]
	v_lshlrev_b32_e32 v40, 16, v137
	v_and_b32_e32 v41, 0xffff0000, v137
	s_mov_b64 s[8:9], 0x90000
	v_pk_add_f32 v[54:55], v[42:43], v[40:41]
	s_waitcnt lgkmcnt(0)
	v_lshl_add_u64 v[48:49], v[212:213], 0, s[8:9]
	v_cvt_pk_bf16_f32 v40, v44, v45
	v_cvt_pk_bf16_f32 v41, v46, v47
	v_cvt_pk_bf16_f32 v42, v52, v53
	v_cvt_pk_bf16_f32 v43, v54, v55
	global_store_dwordx4 v[48:49], v[40:43], off sc1
	v_lshlrev_b32_e32 v48, 16, v130
	v_and_b32_e32 v49, 0xffff0000, v130
	v_pk_add_f32 v[36:37], v[36:37], v[48:49]
	v_lshlrev_b32_e32 v48, 16, v131
	v_and_b32_e32 v49, 0xffff0000, v131
	v_pk_add_f32 v[38:39], v[38:39], v[48:49]
	v_lshlrev_b32_e32 v48, 16, v132
	v_and_b32_e32 v49, 0xffff0000, v132
	v_pk_add_f32 v[48:49], v[32:33], v[48:49]
	v_lshlrev_b32_e32 v32, 16, v133
	v_and_b32_e32 v33, 0xffff0000, v133
	s_mov_b64 s[8:9], 0x90100
	v_pk_mul_f32 v[40:41], v[44:45], v[44:45]
	v_pk_mul_f32 v[44:45], v[52:53], v[52:53]
	v_pk_add_f32 v[52:53], v[34:35], v[32:33]
	v_lshl_add_u64 v[50:51], v[212:213], 0, s[8:9]
	v_cvt_pk_bf16_f32 v32, v36, v37
	v_cvt_pk_bf16_f32 v33, v38, v39
	v_cvt_pk_bf16_f32 v34, v48, v49
	v_cvt_pk_bf16_f32 v35, v52, v53
	global_store_dwordx4 v[50:51], v[32:35], off sc1
	v_pk_mul_f32 v[42:43], v[46:47], v[46:47]
	v_pk_mul_f32 v[46:47], v[54:55], v[54:55]
	v_pk_mul_f32 v[32:33], v[36:37], v[36:37]
	v_pk_mul_f32 v[34:35], v[38:39], v[38:39]
	v_add_f32_e32 v32, v32, v33
	v_add_f32_e32 v34, v34, v35
	v_pk_mul_f32 v[36:37], v[48:49], v[48:49]
	v_pk_mul_f32 v[38:39], v[52:53], v[52:53]
	v_add_f32_e32 v32, v32, v34
	v_add_f32_e32 v33, v46, v47
	v_add_f32_e32 v34, v44, v45
	v_add_f32_e32 v38, v38, v39
	v_add_f32_e32 v36, v36, v37
	v_add_f32_e32 v33, v34, v33
	v_add_f32_e32 v34, v42, v43
	v_add_f32_e32 v35, v40, v41
	v_add_f32_e32 v36, v36, v38
	v_add_f32_e32 v34, v35, v34
	v_add_f32_e32 v32, v32, v36
	v_add_f32_e32 v33, v34, v33
	v_add_f32_e32 v32, v33, v32
	v_mov_b32_e32 v242, v32
	v_mov_b32_e32 v243, v32
	s_nop 1
	v_permlane16_swap_b32_e32 v242, v243
	v_add_f32_e32 v32, v242, v243
	v_mov_b32_e32 v242, v32
	v_mov_b32_e32 v243, v32
	s_nop 1
	v_permlane32_swap_b32_e32 v242, v243
	s_and_saveexec_b64 s[8:9], s[38:39]
	s_cbranch_execz .LBB0_1633
	s_waitcnt lgkmcnt(0)
	v_add_f32_e32 v32, v242, v243
	v_mul_f32_e32 v32, 0x4b800000, v32
	v_trunc_f32_e32 v32, v32
	v_mul_f32_e32 v33, 0x2f800000, v32
	v_floor_f32_e32 v33, v33
	v_fmac_f32_e32 v32, 0xcf800000, v33
	v_cvt_u32_f32_e32 v32, v32
	v_cvt_u32_f32_e32 v33, v33
	v_lshl_add_u64 v[34:35], v[210:211], 3, s[44:45]
	global_atomic_add_x2 v[34:35], v[32:33], off offset:1152
.LBB0_1633:
	s_or_b64 exec, exec, s[8:9]
	v_lshlrev_b32_e32 v36, 16, v116
	v_and_b32_e32 v37, 0xffff0000, v116
	v_pk_add_f32 v[28:29], v[28:29], v[36:37]
	v_lshlrev_b32_e32 v36, 16, v117
	v_and_b32_e32 v37, 0xffff0000, v117
	v_pk_add_f32 v[30:31], v[30:31], v[36:37]
	v_lshlrev_b32_e32 v36, 16, v118
	v_and_b32_e32 v37, 0xffff0000, v118
	v_pk_add_f32 v[36:37], v[24:25], v[36:37]
	v_lshlrev_b32_e32 v24, 16, v119
	v_and_b32_e32 v25, 0xffff0000, v119
	s_mov_b64 s[8:9], 0xa0000
	v_pk_add_f32 v[38:39], v[26:27], v[24:25]
	s_waitcnt lgkmcnt(0)
	v_lshl_add_u64 v[32:33], v[212:213], 0, s[8:9]
	v_cvt_pk_bf16_f32 v24, v28, v29
	v_cvt_pk_bf16_f32 v25, v30, v31
	v_cvt_pk_bf16_f32 v26, v36, v37
	v_cvt_pk_bf16_f32 v27, v38, v39
	global_store_dwordx4 v[32:33], v[24:27], off sc1
	v_lshlrev_b32_e32 v32, 16, v104
	v_and_b32_e32 v33, 0xffff0000, v104
	v_pk_add_f32 v[20:21], v[20:21], v[32:33]
	v_lshlrev_b32_e32 v32, 16, v105
	v_and_b32_e32 v33, 0xffff0000, v105
	v_pk_add_f32 v[22:23], v[22:23], v[32:33]
	v_lshlrev_b32_e32 v32, 16, v106
	v_and_b32_e32 v33, 0xffff0000, v106
	v_pk_add_f32 v[32:33], v[16:17], v[32:33]
	v_lshlrev_b32_e32 v16, 16, v107
	v_and_b32_e32 v17, 0xffff0000, v107
	s_mov_b64 s[8:9], 0xa0100
	v_pk_mul_f32 v[24:25], v[28:29], v[28:29]
	v_pk_mul_f32 v[28:29], v[36:37], v[36:37]
	v_pk_add_f32 v[36:37], v[18:19], v[16:17]
	v_lshl_add_u64 v[34:35], v[212:213], 0, s[8:9]
	v_cvt_pk_bf16_f32 v16, v20, v21
	v_cvt_pk_bf16_f32 v17, v22, v23
	v_cvt_pk_bf16_f32 v18, v32, v33
	v_cvt_pk_bf16_f32 v19, v36, v37
	global_store_dwordx4 v[34:35], v[16:19], off sc1
	v_pk_mul_f32 v[26:27], v[30:31], v[30:31]
	v_pk_mul_f32 v[30:31], v[38:39], v[38:39]
	v_pk_mul_f32 v[16:17], v[20:21], v[20:21]
	v_pk_mul_f32 v[18:19], v[22:23], v[22:23]
	v_add_f32_e32 v16, v16, v17
	v_add_f32_e32 v18, v18, v19
	v_pk_mul_f32 v[20:21], v[32:33], v[32:33]
	v_pk_mul_f32 v[22:23], v[36:37], v[36:37]
	v_add_f32_e32 v16, v16, v18
	v_add_f32_e32 v17, v30, v31
	v_add_f32_e32 v18, v28, v29
	v_add_f32_e32 v22, v22, v23
	v_add_f32_e32 v20, v20, v21
	v_add_f32_e32 v17, v18, v17
	v_add_f32_e32 v18, v26, v27
	v_add_f32_e32 v19, v24, v25
	v_add_f32_e32 v20, v20, v22
	v_add_f32_e32 v18, v19, v18
	v_add_f32_e32 v16, v16, v20
	v_add_f32_e32 v17, v18, v17
	v_add_f32_e32 v16, v17, v16
	v_mov_b32_e32 v242, v16
	v_mov_b32_e32 v243, v16
	s_nop 1
	v_permlane16_swap_b32_e32 v242, v243
	v_add_f32_e32 v16, v242, v243
	v_mov_b32_e32 v242, v16
	v_mov_b32_e32 v243, v16
	s_nop 1
	v_permlane32_swap_b32_e32 v242, v243
	s_and_saveexec_b64 s[8:9], s[38:39]
	s_cbranch_execz .LBB0_1635
	s_waitcnt lgkmcnt(0)
	v_add_f32_e32 v16, v242, v243
	v_mul_f32_e32 v16, 0x4b800000, v16
	v_trunc_f32_e32 v16, v16
	v_mul_f32_e32 v17, 0x2f800000, v16
	v_floor_f32_e32 v17, v17
	v_fmac_f32_e32 v16, 0xcf800000, v17
	v_cvt_u32_f32_e32 v16, v16
	v_cvt_u32_f32_e32 v17, v17
	v_lshl_add_u64 v[18:19], v[210:211], 3, s[44:45]
	global_atomic_add_x2 v[18:19], v[16:17], off offset:1280
.LBB0_1635:
	s_or_b64 exec, exec, s[8:9]
	v_lshlrev_b32_e32 v20, 16, v92
	v_and_b32_e32 v21, 0xffff0000, v92
	v_pk_add_f32 v[12:13], v[12:13], v[20:21]
	v_lshlrev_b32_e32 v20, 16, v93
	v_and_b32_e32 v21, 0xffff0000, v93
	v_pk_add_f32 v[14:15], v[14:15], v[20:21]
	v_lshlrev_b32_e32 v20, 16, v94
	v_and_b32_e32 v21, 0xffff0000, v94
	v_pk_add_f32 v[20:21], v[8:9], v[20:21]
	v_lshlrev_b32_e32 v8, 16, v95
	v_and_b32_e32 v9, 0xffff0000, v95
	s_mov_b64 s[8:9], 0xb0000
	v_pk_add_f32 v[22:23], v[10:11], v[8:9]
	s_waitcnt lgkmcnt(0)
	v_lshl_add_u64 v[16:17], v[212:213], 0, s[8:9]
	v_cvt_pk_bf16_f32 v8, v12, v13
	v_cvt_pk_bf16_f32 v9, v14, v15
	v_cvt_pk_bf16_f32 v10, v20, v21
	v_cvt_pk_bf16_f32 v11, v22, v23
	global_store_dwordx4 v[16:17], v[8:11], off sc1
	v_lshlrev_b32_e32 v16, 16, v88
	v_and_b32_e32 v17, 0xffff0000, v88
	v_pk_add_f32 v[4:5], v[4:5], v[16:17]
	v_lshlrev_b32_e32 v16, 16, v89
	v_and_b32_e32 v17, 0xffff0000, v89
	v_pk_add_f32 v[6:7], v[6:7], v[16:17]
	v_lshlrev_b32_e32 v16, 16, v90
	v_and_b32_e32 v17, 0xffff0000, v90
	v_pk_add_f32 v[16:17], v[0:1], v[16:17]
	v_lshlrev_b32_e32 v0, 16, v91
	v_and_b32_e32 v1, 0xffff0000, v91
	s_mov_b64 s[8:9], 0xb0100
	v_pk_mul_f32 v[8:9], v[12:13], v[12:13]
	v_pk_mul_f32 v[12:13], v[20:21], v[20:21]
	v_pk_add_f32 v[20:21], v[2:3], v[0:1]
	v_lshl_add_u64 v[18:19], v[212:213], 0, s[8:9]
	v_cvt_pk_bf16_f32 v0, v4, v5
	v_cvt_pk_bf16_f32 v1, v6, v7
	v_cvt_pk_bf16_f32 v2, v16, v17
	v_cvt_pk_bf16_f32 v3, v20, v21
	global_store_dwordx4 v[18:19], v[0:3], off sc1
	v_pk_mul_f32 v[10:11], v[14:15], v[14:15]
	v_pk_mul_f32 v[14:15], v[22:23], v[22:23]
	v_pk_mul_f32 v[0:1], v[4:5], v[4:5]
	v_pk_mul_f32 v[2:3], v[6:7], v[6:7]
	v_add_f32_e32 v0, v0, v1
	v_add_f32_e32 v2, v2, v3
	v_pk_mul_f32 v[4:5], v[16:17], v[16:17]
	v_pk_mul_f32 v[6:7], v[20:21], v[20:21]
	v_add_f32_e32 v0, v0, v2
	v_add_f32_e32 v1, v14, v15
	v_add_f32_e32 v2, v12, v13
	v_add_f32_e32 v6, v6, v7
	v_add_f32_e32 v4, v4, v5
	v_add_f32_e32 v1, v2, v1
	v_add_f32_e32 v2, v10, v11
	v_add_f32_e32 v3, v8, v9
	v_add_f32_e32 v4, v4, v6
	v_add_f32_e32 v2, v3, v2
	v_add_f32_e32 v0, v0, v4
	v_add_f32_e32 v1, v2, v1
	v_add_f32_e32 v0, v1, v0
	v_mov_b32_e32 v242, v0
	v_mov_b32_e32 v243, v0
	s_nop 1
	v_permlane16_swap_b32_e32 v242, v243
	v_add_f32_e32 v0, v242, v243
	v_mov_b32_e32 v242, v0
	v_mov_b32_e32 v243, v0
	s_nop 1
	v_permlane32_swap_b32_e32 v242, v243
	s_and_saveexec_b64 s[8:9], s[38:39]
	s_cbranch_execz .LBB0_1637
	s_waitcnt lgkmcnt(0)
	v_add_f32_e32 v0, v242, v243
	v_mul_f32_e32 v0, 0x4b800000, v0
	v_trunc_f32_e32 v0, v0
	v_mul_f32_e32 v1, 0x2f800000, v0
	v_floor_f32_e32 v1, v1
	v_fmac_f32_e32 v0, 0xcf800000, v1
	v_cvt_u32_f32_e32 v0, v0
	v_cvt_u32_f32_e32 v1, v1
	v_lshl_add_u64 v[2:3], v[210:211], 3, s[44:45]
	global_atomic_add_x2 v[2:3], v[0:1], off offset:1408
